# gemm_in and ffn_in: next double tile's first k-step is issued before the two epilogue passes
# speedup vs baseline: 1.0008x; 1.0008x over previous
.LBB0_209:
	s_not_b32 s2, s5
	s_add_i32 s2, s8, s2
	s_add_i32 s2, s2, s17
	s_ashr_i32 s3, s2, 31
	s_abs_i32 s2, s2
	s_mul_hi_u32 s5, s2, s72
	s_mul_i32 s8, s5, s4
	s_sub_i32 s2, s2, s8
	s_xor_b32 s3, s3, s16
	s_add_i32 s8, s5, 1
	s_sub_i32 s9, s2, s4
	s_cmp_ge_u32 s2, s4
	s_cselect_b32 s5, s8, s5
	s_cselect_b32 s2, s9, s2
	s_add_i32 s8, s5, 1
	s_cmp_ge_u32 s2, s4
	s_cselect_b32 s2, s8, s5
	s_xor_b32 s2, s2, s3
	s_sub_i32 s2, s2, s3
	s_add_i32 s3, s15, s24
	s_not_b32 s4, s23
	s_add_i32 s4, s4, s3
	s_ashr_i32 s3, s4, 31
	s_abs_i32 s4, s4
	s_mul_i32 s1, s4, s1
	s_mul_hi_u32 s0, s4, s0
	s_add_i32 s0, s0, s1
	s_mul_i32 s1, s0, s12
	s_sub_i32 s1, s4, s1
	s_xor_b32 s3, s3, s13
	s_add_i32 s4, s0, 1
	s_sub_i32 s5, s1, s12
	s_cmp_ge_u32 s1, s12
	s_cselect_b32 s0, s4, s0
	s_cselect_b32 s1, s5, s1
	s_add_i32 s4, s0, 1
	s_cmp_ge_u32 s1, s12
	s_cselect_b32 s0, s4, s0
	s_xor_b32 s0, s0, s3
	s_sub_i32 s3, s0, s3
	s_cmp_lt_i32 s22, 0
	s_cselect_b64 s[8:9], -1, 0
	s_and_b64 s[0:1], s[8:9], exec
	s_cselect_b32 s26, s3, s2
	s_not_b32 s0, s14
	s_lshr_b32 s0, s0, 31
	s_add_i32 s26, s26, s0
	s_cmp_lt_i32 s26, 1
	s_cbranch_scc1 .LBB0_476
	s_lshr_b32 s27, s10, 3
	s_cmp_lt_i32 s14, 0
	s_mul_hi_u32 s0, s14, 0x3521cfb3
	s_cselect_b64 s[10:11], -1, 0
	s_sub_i32 s2, s14, s0
	s_lshr_b32 s2, s2, 1
	s_add_i32 s2, s2, s0
	s_lshr_b32 s0, s2, 5
	s_add_i32 s28, s0, 0x80
	s_mul_i32 s0, s0, 53
	v_and_b32_e32 v2, 15, v0
	s_sub_i32 s29, s14, s0
	v_ashrrev_i32_e32 v3, 1, v0
	s_movk_i32 s0, 0xffc0
	v_and_or_b32 v87, v3, s0, v2
	v_lshrrev_b32_e32 v2, 2, v0
	v_and_b32_e32 v2, 12, v2
	v_and_or_b32 v86, v0, 64, v2
	v_and_b32_e32 v0, 64, v0
	v_cmp_ne_u32_e64 s[40:41], 0, v0
	v_or_b32_e32 v0, 16, v86
	v_cmp_gt_u32_e64 s[44:45], 40, v0
	v_or_b32_e32 v0, 32, v86
	v_cmp_gt_u32_e64 s[4:5], 40, v0
	v_cvt_f32_u32_e32 v0, s25
	v_readlane_b32 s2, v249, 52
	s_load_dwordx2 s[12:13], s[6:7], 0x138
	s_load_dwordx2 s[14:15], s[6:7], 0xe0
	s_lshl_b32 s0, s2, 8
	v_rcp_iflag_f32_e32 v0, v0
	s_or_b32 s30, s0, 0xffffc000
	s_sub_i32 s0, 0, s25
	s_mov_b32 s18, s2
	v_mul_f32_e32 v0, 0x4f7ffffe, v0
	v_cvt_u32_f32_e32 v0, v0
	v_readlane_b32 s3, v249, 53
	s_mul_i32 s72, s2, 0xc00
	s_lshl_b32 s31, s2, 14
	v_readfirstlane_b32 s16, v0
	s_mul_i32 s0, s0, s16
	s_mul_hi_u32 s0, s16, s0
	s_lshl_b32 s2, s2, 6
	s_add_i32 s33, s16, s0
	s_mul_i32 s16, s18, 0xd40000
	s_mov_b32 s3, s73
	s_mul_hi_u32 s0, s18, 0xd40000
	s_waitcnt lgkmcnt(0)
	s_add_u32 s34, s14, s16
	s_mov_b32 s1, 0
	v_or_b32_e32 v104, 0xfffff180, v86
	v_cmp_gt_u32_e64 s[42:43], 40, v86
	s_addc_u32 s35, s15, s0
	s_lshl_b64 s[16:17], s[72:73], 2
	s_lshl_b64 s[18:19], s[2:3], 2
	v_lshlrev_b32_e32 v105, 2, v2
	s_mov_b32 s32, 0
	v_readlane_b32 s2, v249, 1
	s_nop 0
	s_cmpk_lg_u32 s2, 0x200
	s_cbranch_scc1 .LBB0_212
	s_mov_b32 s48, 0
	v_readlane_b32 s2, v249, 0
	s_nop 0
	s_and_b32 s3, s2, 7
	s_lshr_b32 s2, s2, 3
	s_cmp_lt_u32 s2, 40
	s_cselect_b32 s38, 7, 6
	s_cmp_lt_u32 s48, s38
	s_cbranch_scc0 .Lg2_c0_extra
	s_lshl_b32 s20, s48, 6
	s_add_i32 s20, s20, s2
	s_cmp_ge_u32 s20, 0xd4
	s_cselect_b32 s21, 1, 0
	s_mul_i32 s0, s21, 0xd4
	s_sub_i32 s20, s20, s0
	s_lshr_b32 s37, s20, 2
	s_and_b32 s20, s20, 3
	s_lshl_b32 s21, s21, 3
	s_add_i32 s20, s20, s21
	s_lshl_b32 s20, s20, 3
	s_add_i32 s0, s20, s3
	s_add_i32 s49, s0, 32
	s_branch .Lg2_c0_have

.Lg2_c0_have:
	s_mov_b32 s65, 1
.Lg2_setup:
	s_lshl_b32 s72, s37, 7
	v_and_b32_e32 v70, 7, v196
	v_bfe_u32 v71, v196, 4, 2
	v_bfe_u32 v72, v196, 6, 1
	v_lshl_or_b32 v73, v72, 2, v71
	v_xor_b32_e32 v70, v70, v73
	v_lshrrev_b32_e32 v73, 3, v196
	v_lshlrev_b32_e32 v73, 11, v73
	v_lshl_or_b32 v74, v70, 4, v73
	v_add_u32_e32 v75, 0x10000, v74
	v_add_u32_e32 v76, 0x20000, v74
	v_add_u32_e32 v77, 0x30000, v74
	v_and_b32_e32 v70, 15, v196
	v_bfe_u32 v73, v196, 1, 3
	v_xor_b32_e32 v73, v71, v73
	v_lshlrev_b32_e32 v73, 4, v73
	v_xor_b32_e32 v83, 64, v73
	v_lshlrev_b32_e32 v70, 7, v70
	v_lshrrev_b32_e32 v84, 7, v196
	v_lshl_or_b32 v84, v84, 13, v70
	v_lshl_or_b32 v85, v72, 13, v70
	v_add_u32_e32 v78, v84, v73
	v_add_u32_e32 v80, v84, v83
	v_add_u32_e32 v79, v85, v73
	v_add_u32_e32 v81, v85, v83
	v_readfirstlane_b32 s58, v196
	s_lshr_b32 s58, s58, 6
	s_lshl_b32 s58, s58, 10
	s_cmp_eq_u32 s65, 2
	s_cbranch_scc1 .Lg2_loop
	s_lshl_b32 s2, s0, 18
	s_add_u32 s50, s12, s2
	s_addc_u32 s51, s13, 0
	s_lshl_b32 s2, s49, 18
	s_add_u32 s52, s12, s2
	s_addc_u32 s53, s13, 0
	s_lshl_b32 s2, s37, 18
	s_add_u32 s56, s34, s2
	s_addc_u32 s57, s35, 0
	s_barrier
	s_add_i32 m0, s58, 0x0
	s_nop 0
	global_load_lds_dwordx4 v74, s[50:51]
	s_add_i32 m0, s58, 0x1000
	s_nop 0
	global_load_lds_dwordx4 v75, s[50:51]
	s_add_i32 m0, s58, 0x2000
	s_nop 0
	global_load_lds_dwordx4 v76, s[50:51]
	s_add_i32 m0, s58, 0x3000
	s_nop 0
	global_load_lds_dwordx4 v77, s[50:51]
	s_add_i32 m0, s58, 0x4000
	s_nop 0
	global_load_lds_dwordx4 v74, s[52:53]
	s_add_i32 m0, s58, 0x5000
	s_nop 0
	global_load_lds_dwordx4 v75, s[52:53]
	s_add_i32 m0, s58, 0x6000
	s_nop 0
	global_load_lds_dwordx4 v76, s[52:53]
	s_add_i32 m0, s58, 0x7000
	s_nop 0
	global_load_lds_dwordx4 v77, s[52:53]
	s_add_u32 s50, s50, 0x80
	s_addc_u32 s51, s51, 0
	s_add_u32 s52, s52, 0x80
	s_addc_u32 s53, s53, 0
	s_add_i32 m0, s58, 0x8000
	s_nop 0
	global_load_lds_dwordx4 v74, s[56:57]
	s_add_i32 m0, s58, 0x9000
	s_nop 0
	global_load_lds_dwordx4 v75, s[56:57]
	s_add_i32 m0, s58, 0xa000
	s_nop 0
	global_load_lds_dwordx4 v76, s[56:57]
	s_add_i32 m0, s58, 0xb000
	s_nop 0
	global_load_lds_dwordx4 v77, s[56:57]
	s_add_u32 s56, s56, 0x80
	s_addc_u32 s57, s57, 0
.Lg2_loop:
	v_mov_b64_e32 v[62:63], 0
	v_mov_b64_e32 v[64:65], 0
	v_mov_b64_e32 v[58:59], 0
	v_mov_b64_e32 v[60:61], 0
	v_mov_b64_e32 v[54:55], 0
	v_mov_b64_e32 v[56:57], 0
	v_mov_b64_e32 v[50:51], 0
	v_mov_b64_e32 v[52:53], 0
	v_mov_b64_e32 v[46:47], 0
	v_mov_b64_e32 v[48:49], 0
	v_mov_b64_e32 v[42:43], 0
	v_mov_b64_e32 v[44:45], 0
	v_mov_b64_e32 v[38:39], 0
	v_mov_b64_e32 v[40:41], 0
	v_mov_b64_e32 v[34:35], 0
	v_mov_b64_e32 v[36:37], 0
	v_mov_b64_e32 v[30:31], 0
	v_mov_b64_e32 v[32:33], 0
	v_mov_b64_e32 v[26:27], 0
	v_mov_b64_e32 v[28:29], 0
	v_mov_b64_e32 v[22:23], 0
	v_mov_b64_e32 v[24:25], 0
	v_mov_b64_e32 v[18:19], 0
	v_mov_b64_e32 v[20:21], 0
	v_mov_b64_e32 v[14:15], 0
	v_mov_b64_e32 v[16:17], 0
	v_mov_b64_e32 v[10:11], 0
	v_mov_b64_e32 v[12:13], 0
	v_mov_b64_e32 v[6:7], 0
	v_mov_b64_e32 v[8:9], 0
	v_mov_b64_e32 v[2:3], 0
	v_mov_b64_e32 v[4:5], 0
	v_mov_b64_e32 v[66:67], 0
	v_mov_b64_e32 v[68:69], 0
	v_mov_b64_e32 v[70:71], 0
	v_mov_b64_e32 v[72:73], 0
	v_mov_b64_e32 v[82:83], 0
	v_mov_b64_e32 v[84:85], 0
	v_mov_b64_e32 v[88:89], 0
	v_mov_b64_e32 v[90:91], 0
	v_mov_b64_e32 v[92:93], 0
	v_mov_b64_e32 v[94:95], 0
	v_mov_b64_e32 v[96:97], 0
	v_mov_b64_e32 v[98:99], 0
	v_mov_b64_e32 v[100:101], 0
	v_mov_b64_e32 v[102:103], 0
	v_mov_b64_e32 v[106:107], 0
	v_mov_b64_e32 v[108:109], 0
	v_mov_b64_e32 v[110:111], 0
	v_mov_b64_e32 v[112:113], 0
	v_mov_b64_e32 v[114:115], 0
	v_mov_b64_e32 v[116:117], 0
	v_mov_b64_e32 v[118:119], 0
	v_mov_b64_e32 v[120:121], 0
	v_mov_b64_e32 v[122:123], 0
	v_mov_b64_e32 v[124:125], 0
	v_mov_b64_e32 v[126:127], 0
	v_mov_b64_e32 v[128:129], 0
	v_mov_b64_e32 v[136:137], 0
	v_mov_b64_e32 v[138:139], 0
	v_mov_b64_e32 v[140:141], 0
	v_mov_b64_e32 v[142:143], 0
	v_mov_b64_e32 v[144:145], 0
	v_mov_b64_e32 v[146:147], 0
	s_movk_i32 s59, 7
.Lg2_k:
	s_waitcnt vmcnt(0)
	s_barrier
	s_add_i32 m0, s58, 0xc000
	s_nop 0
	global_load_lds_dwordx4 v74, s[56:57]
	s_add_i32 m0, s58, 0xd000
	s_nop 0
	global_load_lds_dwordx4 v75, s[56:57]
	s_add_i32 m0, s58, 0xe000
	s_nop 0
	global_load_lds_dwordx4 v76, s[56:57]
	s_add_i32 m0, s58, 0xf000
	s_nop 0
	global_load_lds_dwordx4 v77, s[56:57]
	s_add_u32 s56, s56, 0x80
	s_addc_u32 s57, s57, 0
	ds_read_b128 v[148:151], v78 offset:0
	ds_read_b128 v[152:155], v78 offset:2048
	ds_read_b128 v[156:159], v78 offset:4096
	ds_read_b128 v[160:163], v78 offset:6144
	ds_read_b128 v[188:191], v79 offset:32768
	ds_read_b128 v[192:195], v79 offset:34816
	ds_read_b128 v[208:211], v79 offset:36864
	ds_read_b128 v[212:215], v79 offset:38912
	ds_read_b128 v[164:167], v78 offset:16384
	ds_read_b128 v[168:171], v78 offset:18432
	ds_read_b128 v[174:177], v78 offset:20480
	ds_read_b128 v[182:185], v78 offset:22528
	s_setprio 1
	s_waitcnt lgkmcnt(4)
	v_mfma_f32_16x16x32_bf16 v[62:65], v[188:191], v[148:151], v[62:65]
	v_mfma_f32_16x16x32_bf16 v[58:61], v[192:195], v[148:151], v[58:61]
	v_mfma_f32_16x16x32_bf16 v[54:57], v[208:211], v[148:151], v[54:57]
	v_mfma_f32_16x16x32_bf16 v[50:53], v[212:215], v[148:151], v[50:53]
	v_mfma_f32_16x16x32_bf16 v[46:49], v[188:191], v[152:155], v[46:49]
	v_mfma_f32_16x16x32_bf16 v[42:45], v[192:195], v[152:155], v[42:45]
	v_mfma_f32_16x16x32_bf16 v[38:41], v[208:211], v[152:155], v[38:41]
	v_mfma_f32_16x16x32_bf16 v[34:37], v[212:215], v[152:155], v[34:37]
	v_mfma_f32_16x16x32_bf16 v[30:33], v[188:191], v[156:159], v[30:33]
	v_mfma_f32_16x16x32_bf16 v[26:29], v[192:195], v[156:159], v[26:29]
	v_mfma_f32_16x16x32_bf16 v[22:25], v[208:211], v[156:159], v[22:25]
	v_mfma_f32_16x16x32_bf16 v[18:21], v[212:215], v[156:159], v[18:21]
	v_mfma_f32_16x16x32_bf16 v[14:17], v[188:191], v[160:163], v[14:17]
	v_mfma_f32_16x16x32_bf16 v[10:13], v[192:195], v[160:163], v[10:13]
	v_mfma_f32_16x16x32_bf16 v[6:9], v[208:211], v[160:163], v[6:9]
	v_mfma_f32_16x16x32_bf16 v[2:5], v[212:215], v[160:163], v[2:5]
	s_waitcnt lgkmcnt(0)
	v_mfma_f32_16x16x32_bf16 v[66:69], v[188:191], v[164:167], v[66:69]
	v_mfma_f32_16x16x32_bf16 v[70:73], v[192:195], v[164:167], v[70:73]
	v_mfma_f32_16x16x32_bf16 v[82:85], v[208:211], v[164:167], v[82:85]
	v_mfma_f32_16x16x32_bf16 v[88:91], v[212:215], v[164:167], v[88:91]
	v_mfma_f32_16x16x32_bf16 v[92:95], v[188:191], v[168:171], v[92:95]
	v_mfma_f32_16x16x32_bf16 v[96:99], v[192:195], v[168:171], v[96:99]
	v_mfma_f32_16x16x32_bf16 v[100:103], v[208:211], v[168:171], v[100:103]
	v_mfma_f32_16x16x32_bf16 v[106:109], v[212:215], v[168:171], v[106:109]
	v_mfma_f32_16x16x32_bf16 v[110:113], v[188:191], v[174:177], v[110:113]
	v_mfma_f32_16x16x32_bf16 v[114:117], v[192:195], v[174:177], v[114:117]
	v_mfma_f32_16x16x32_bf16 v[118:121], v[208:211], v[174:177], v[118:121]
	v_mfma_f32_16x16x32_bf16 v[122:125], v[212:215], v[174:177], v[122:125]
	v_mfma_f32_16x16x32_bf16 v[126:129], v[188:191], v[182:185], v[126:129]
	v_mfma_f32_16x16x32_bf16 v[136:139], v[192:195], v[182:185], v[136:139]
	v_mfma_f32_16x16x32_bf16 v[140:143], v[208:211], v[182:185], v[140:143]
	v_mfma_f32_16x16x32_bf16 v[144:147], v[212:215], v[182:185], v[144:147]
	s_setprio 0
	ds_read_b128 v[148:151], v80 offset:0
	ds_read_b128 v[152:155], v80 offset:2048
	ds_read_b128 v[156:159], v80 offset:4096
	ds_read_b128 v[160:163], v80 offset:6144
	ds_read_b128 v[188:191], v81 offset:32768
	ds_read_b128 v[192:195], v81 offset:34816
	ds_read_b128 v[208:211], v81 offset:36864
	ds_read_b128 v[212:215], v81 offset:38912
	ds_read_b128 v[164:167], v80 offset:16384
	ds_read_b128 v[168:171], v80 offset:18432
	ds_read_b128 v[174:177], v80 offset:20480
	ds_read_b128 v[182:185], v80 offset:22528
	s_waitcnt lgkmcnt(0)
	s_barrier
	s_add_i32 m0, s58, 0x0
	s_nop 0
	global_load_lds_dwordx4 v74, s[50:51]
	s_add_i32 m0, s58, 0x1000
	s_nop 0
	global_load_lds_dwordx4 v75, s[50:51]
	s_add_i32 m0, s58, 0x2000
	s_nop 0
	global_load_lds_dwordx4 v76, s[50:51]
	s_add_i32 m0, s58, 0x3000
	s_nop 0
	global_load_lds_dwordx4 v77, s[50:51]
	s_add_i32 m0, s58, 0x4000
	s_nop 0
	global_load_lds_dwordx4 v74, s[52:53]
	s_add_i32 m0, s58, 0x5000
	s_nop 0
	global_load_lds_dwordx4 v75, s[52:53]
	s_add_i32 m0, s58, 0x6000
	s_nop 0
	global_load_lds_dwordx4 v76, s[52:53]
	s_add_i32 m0, s58, 0x7000
	s_nop 0
	global_load_lds_dwordx4 v77, s[52:53]
	s_add_u32 s50, s50, 0x80
	s_addc_u32 s51, s51, 0
	s_add_u32 s52, s52, 0x80
	s_addc_u32 s53, s53, 0
	s_setprio 1
	v_mfma_f32_16x16x32_bf16 v[62:65], v[188:191], v[148:151], v[62:65]
	v_mfma_f32_16x16x32_bf16 v[58:61], v[192:195], v[148:151], v[58:61]
	v_mfma_f32_16x16x32_bf16 v[54:57], v[208:211], v[148:151], v[54:57]
	v_mfma_f32_16x16x32_bf16 v[50:53], v[212:215], v[148:151], v[50:53]
	v_mfma_f32_16x16x32_bf16 v[46:49], v[188:191], v[152:155], v[46:49]
	v_mfma_f32_16x16x32_bf16 v[42:45], v[192:195], v[152:155], v[42:45]
	v_mfma_f32_16x16x32_bf16 v[38:41], v[208:211], v[152:155], v[38:41]
	v_mfma_f32_16x16x32_bf16 v[34:37], v[212:215], v[152:155], v[34:37]
	v_mfma_f32_16x16x32_bf16 v[30:33], v[188:191], v[156:159], v[30:33]
	v_mfma_f32_16x16x32_bf16 v[26:29], v[192:195], v[156:159], v[26:29]
	v_mfma_f32_16x16x32_bf16 v[22:25], v[208:211], v[156:159], v[22:25]
	v_mfma_f32_16x16x32_bf16 v[18:21], v[212:215], v[156:159], v[18:21]
	v_mfma_f32_16x16x32_bf16 v[14:17], v[188:191], v[160:163], v[14:17]
	v_mfma_f32_16x16x32_bf16 v[10:13], v[192:195], v[160:163], v[10:13]
	v_mfma_f32_16x16x32_bf16 v[6:9], v[208:211], v[160:163], v[6:9]
	v_mfma_f32_16x16x32_bf16 v[2:5], v[212:215], v[160:163], v[2:5]
	v_mfma_f32_16x16x32_bf16 v[66:69], v[188:191], v[164:167], v[66:69]
	v_mfma_f32_16x16x32_bf16 v[70:73], v[192:195], v[164:167], v[70:73]
	v_mfma_f32_16x16x32_bf16 v[82:85], v[208:211], v[164:167], v[82:85]
	v_mfma_f32_16x16x32_bf16 v[88:91], v[212:215], v[164:167], v[88:91]
	v_mfma_f32_16x16x32_bf16 v[92:95], v[188:191], v[168:171], v[92:95]
	v_mfma_f32_16x16x32_bf16 v[96:99], v[192:195], v[168:171], v[96:99]
	v_mfma_f32_16x16x32_bf16 v[100:103], v[208:211], v[168:171], v[100:103]
	v_mfma_f32_16x16x32_bf16 v[106:109], v[212:215], v[168:171], v[106:109]
	v_mfma_f32_16x16x32_bf16 v[110:113], v[188:191], v[174:177], v[110:113]
	v_mfma_f32_16x16x32_bf16 v[114:117], v[192:195], v[174:177], v[114:117]
	v_mfma_f32_16x16x32_bf16 v[118:121], v[208:211], v[174:177], v[118:121]
	v_mfma_f32_16x16x32_bf16 v[122:125], v[212:215], v[174:177], v[122:125]
	v_mfma_f32_16x16x32_bf16 v[126:129], v[188:191], v[182:185], v[126:129]
	v_mfma_f32_16x16x32_bf16 v[136:139], v[192:195], v[182:185], v[136:139]
	v_mfma_f32_16x16x32_bf16 v[140:143], v[208:211], v[182:185], v[140:143]
	v_mfma_f32_16x16x32_bf16 v[144:147], v[212:215], v[182:185], v[144:147]
	s_setprio 0
	s_waitcnt vmcnt(0)
	s_barrier
	s_add_i32 m0, s58, 0x8000
	s_nop 0
	global_load_lds_dwordx4 v74, s[56:57]
	s_add_i32 m0, s58, 0x9000
	s_nop 0
	global_load_lds_dwordx4 v75, s[56:57]
	s_add_i32 m0, s58, 0xa000
	s_nop 0
	global_load_lds_dwordx4 v76, s[56:57]
	s_add_i32 m0, s58, 0xb000
	s_nop 0
	global_load_lds_dwordx4 v77, s[56:57]
	s_add_u32 s56, s56, 0x80
	s_addc_u32 s57, s57, 0
	ds_read_b128 v[148:151], v78 offset:0
	ds_read_b128 v[152:155], v78 offset:2048
	ds_read_b128 v[156:159], v78 offset:4096
	ds_read_b128 v[160:163], v78 offset:6144
	ds_read_b128 v[188:191], v79 offset:49152
	ds_read_b128 v[192:195], v79 offset:51200
	ds_read_b128 v[208:211], v79 offset:53248
	ds_read_b128 v[212:215], v79 offset:55296
	ds_read_b128 v[164:167], v78 offset:16384
	ds_read_b128 v[168:171], v78 offset:18432
	ds_read_b128 v[174:177], v78 offset:20480
	ds_read_b128 v[182:185], v78 offset:22528
	s_setprio 1
	s_waitcnt lgkmcnt(4)
	v_mfma_f32_16x16x32_bf16 v[62:65], v[188:191], v[148:151], v[62:65]
	v_mfma_f32_16x16x32_bf16 v[58:61], v[192:195], v[148:151], v[58:61]
	v_mfma_f32_16x16x32_bf16 v[54:57], v[208:211], v[148:151], v[54:57]
	v_mfma_f32_16x16x32_bf16 v[50:53], v[212:215], v[148:151], v[50:53]
	v_mfma_f32_16x16x32_bf16 v[46:49], v[188:191], v[152:155], v[46:49]
	v_mfma_f32_16x16x32_bf16 v[42:45], v[192:195], v[152:155], v[42:45]
	v_mfma_f32_16x16x32_bf16 v[38:41], v[208:211], v[152:155], v[38:41]
	v_mfma_f32_16x16x32_bf16 v[34:37], v[212:215], v[152:155], v[34:37]
	v_mfma_f32_16x16x32_bf16 v[30:33], v[188:191], v[156:159], v[30:33]
	v_mfma_f32_16x16x32_bf16 v[26:29], v[192:195], v[156:159], v[26:29]
	v_mfma_f32_16x16x32_bf16 v[22:25], v[208:211], v[156:159], v[22:25]
	v_mfma_f32_16x16x32_bf16 v[18:21], v[212:215], v[156:159], v[18:21]
	v_mfma_f32_16x16x32_bf16 v[14:17], v[188:191], v[160:163], v[14:17]
	v_mfma_f32_16x16x32_bf16 v[10:13], v[192:195], v[160:163], v[10:13]
	v_mfma_f32_16x16x32_bf16 v[6:9], v[208:211], v[160:163], v[6:9]
	v_mfma_f32_16x16x32_bf16 v[2:5], v[212:215], v[160:163], v[2:5]
	s_waitcnt lgkmcnt(0)
	v_mfma_f32_16x16x32_bf16 v[66:69], v[188:191], v[164:167], v[66:69]
	v_mfma_f32_16x16x32_bf16 v[70:73], v[192:195], v[164:167], v[70:73]
	v_mfma_f32_16x16x32_bf16 v[82:85], v[208:211], v[164:167], v[82:85]
	v_mfma_f32_16x16x32_bf16 v[88:91], v[212:215], v[164:167], v[88:91]
	v_mfma_f32_16x16x32_bf16 v[92:95], v[188:191], v[168:171], v[92:95]
	v_mfma_f32_16x16x32_bf16 v[96:99], v[192:195], v[168:171], v[96:99]
	v_mfma_f32_16x16x32_bf16 v[100:103], v[208:211], v[168:171], v[100:103]
	v_mfma_f32_16x16x32_bf16 v[106:109], v[212:215], v[168:171], v[106:109]
	v_mfma_f32_16x16x32_bf16 v[110:113], v[188:191], v[174:177], v[110:113]
	v_mfma_f32_16x16x32_bf16 v[114:117], v[192:195], v[174:177], v[114:117]
	v_mfma_f32_16x16x32_bf16 v[118:121], v[208:211], v[174:177], v[118:121]
	v_mfma_f32_16x16x32_bf16 v[122:125], v[212:215], v[174:177], v[122:125]
	v_mfma_f32_16x16x32_bf16 v[126:129], v[188:191], v[182:185], v[126:129]
	v_mfma_f32_16x16x32_bf16 v[136:139], v[192:195], v[182:185], v[136:139]
	v_mfma_f32_16x16x32_bf16 v[140:143], v[208:211], v[182:185], v[140:143]
	v_mfma_f32_16x16x32_bf16 v[144:147], v[212:215], v[182:185], v[144:147]
	s_setprio 0
	ds_read_b128 v[148:151], v80 offset:0
	ds_read_b128 v[152:155], v80 offset:2048
	ds_read_b128 v[156:159], v80 offset:4096
	ds_read_b128 v[160:163], v80 offset:6144
	ds_read_b128 v[188:191], v81 offset:49152
	ds_read_b128 v[192:195], v81 offset:51200
	ds_read_b128 v[208:211], v81 offset:53248
	ds_read_b128 v[212:215], v81 offset:55296
	ds_read_b128 v[164:167], v80 offset:16384
	ds_read_b128 v[168:171], v80 offset:18432
	ds_read_b128 v[174:177], v80 offset:20480
	ds_read_b128 v[182:185], v80 offset:22528
	s_waitcnt lgkmcnt(0)
	s_barrier
	s_add_i32 m0, s58, 0x0
	s_nop 0
	global_load_lds_dwordx4 v74, s[50:51]
	s_add_i32 m0, s58, 0x1000
	s_nop 0
	global_load_lds_dwordx4 v75, s[50:51]
	s_add_i32 m0, s58, 0x2000
	s_nop 0
	global_load_lds_dwordx4 v76, s[50:51]
	s_add_i32 m0, s58, 0x3000
	s_nop 0
	global_load_lds_dwordx4 v77, s[50:51]
	s_add_i32 m0, s58, 0x4000
	s_nop 0
	global_load_lds_dwordx4 v74, s[52:53]
	s_add_i32 m0, s58, 0x5000
	s_nop 0
	global_load_lds_dwordx4 v75, s[52:53]
	s_add_i32 m0, s58, 0x6000
	s_nop 0
	global_load_lds_dwordx4 v76, s[52:53]
	s_add_i32 m0, s58, 0x7000
	s_nop 0
	global_load_lds_dwordx4 v77, s[52:53]
	s_add_u32 s50, s50, 0x80
	s_addc_u32 s51, s51, 0
	s_add_u32 s52, s52, 0x80
	s_addc_u32 s53, s53, 0
	s_setprio 1
	v_mfma_f32_16x16x32_bf16 v[62:65], v[188:191], v[148:151], v[62:65]
	v_mfma_f32_16x16x32_bf16 v[58:61], v[192:195], v[148:151], v[58:61]
	v_mfma_f32_16x16x32_bf16 v[54:57], v[208:211], v[148:151], v[54:57]
	v_mfma_f32_16x16x32_bf16 v[50:53], v[212:215], v[148:151], v[50:53]
	v_mfma_f32_16x16x32_bf16 v[46:49], v[188:191], v[152:155], v[46:49]
	v_mfma_f32_16x16x32_bf16 v[42:45], v[192:195], v[152:155], v[42:45]
	v_mfma_f32_16x16x32_bf16 v[38:41], v[208:211], v[152:155], v[38:41]
	v_mfma_f32_16x16x32_bf16 v[34:37], v[212:215], v[152:155], v[34:37]
	v_mfma_f32_16x16x32_bf16 v[30:33], v[188:191], v[156:159], v[30:33]
	v_mfma_f32_16x16x32_bf16 v[26:29], v[192:195], v[156:159], v[26:29]
	v_mfma_f32_16x16x32_bf16 v[22:25], v[208:211], v[156:159], v[22:25]
	v_mfma_f32_16x16x32_bf16 v[18:21], v[212:215], v[156:159], v[18:21]
	v_mfma_f32_16x16x32_bf16 v[14:17], v[188:191], v[160:163], v[14:17]
	v_mfma_f32_16x16x32_bf16 v[10:13], v[192:195], v[160:163], v[10:13]
	v_mfma_f32_16x16x32_bf16 v[6:9], v[208:211], v[160:163], v[6:9]
	v_mfma_f32_16x16x32_bf16 v[2:5], v[212:215], v[160:163], v[2:5]
	v_mfma_f32_16x16x32_bf16 v[66:69], v[188:191], v[164:167], v[66:69]
	v_mfma_f32_16x16x32_bf16 v[70:73], v[192:195], v[164:167], v[70:73]
	v_mfma_f32_16x16x32_bf16 v[82:85], v[208:211], v[164:167], v[82:85]
	v_mfma_f32_16x16x32_bf16 v[88:91], v[212:215], v[164:167], v[88:91]
	v_mfma_f32_16x16x32_bf16 v[92:95], v[188:191], v[168:171], v[92:95]
	v_mfma_f32_16x16x32_bf16 v[96:99], v[192:195], v[168:171], v[96:99]
	v_mfma_f32_16x16x32_bf16 v[100:103], v[208:211], v[168:171], v[100:103]
	v_mfma_f32_16x16x32_bf16 v[106:109], v[212:215], v[168:171], v[106:109]
	v_mfma_f32_16x16x32_bf16 v[110:113], v[188:191], v[174:177], v[110:113]
	v_mfma_f32_16x16x32_bf16 v[114:117], v[192:195], v[174:177], v[114:117]
	v_mfma_f32_16x16x32_bf16 v[118:121], v[208:211], v[174:177], v[118:121]
	v_mfma_f32_16x16x32_bf16 v[122:125], v[212:215], v[174:177], v[122:125]
	v_mfma_f32_16x16x32_bf16 v[126:129], v[188:191], v[182:185], v[126:129]
	v_mfma_f32_16x16x32_bf16 v[136:139], v[192:195], v[182:185], v[136:139]
	v_mfma_f32_16x16x32_bf16 v[140:143], v[208:211], v[182:185], v[140:143]
	v_mfma_f32_16x16x32_bf16 v[144:147], v[212:215], v[182:185], v[144:147]
	s_setprio 0
	s_add_i32 s59, s59, -1
	s_cmp_lg_u32 s59, 0
	s_cbranch_scc1 .Lg2_k
	s_waitcnt vmcnt(0)
	s_barrier
	s_add_i32 m0, s58, 0xc000
	s_nop 0
	global_load_lds_dwordx4 v74, s[56:57]
	s_add_i32 m0, s58, 0xd000
	s_nop 0
	global_load_lds_dwordx4 v75, s[56:57]
	s_add_i32 m0, s58, 0xe000
	s_nop 0
	global_load_lds_dwordx4 v76, s[56:57]
	s_add_i32 m0, s58, 0xf000
	s_nop 0
	global_load_lds_dwordx4 v77, s[56:57]
	s_add_u32 s56, s56, 0x80
	s_addc_u32 s57, s57, 0
	ds_read_b128 v[148:151], v78 offset:0
	ds_read_b128 v[152:155], v78 offset:2048
	ds_read_b128 v[156:159], v78 offset:4096
	ds_read_b128 v[160:163], v78 offset:6144
	ds_read_b128 v[188:191], v79 offset:32768
	ds_read_b128 v[192:195], v79 offset:34816
	ds_read_b128 v[208:211], v79 offset:36864
	ds_read_b128 v[212:215], v79 offset:38912
	ds_read_b128 v[164:167], v78 offset:16384
	ds_read_b128 v[168:171], v78 offset:18432
	ds_read_b128 v[174:177], v78 offset:20480
	ds_read_b128 v[182:185], v78 offset:22528
	s_setprio 1
	s_waitcnt lgkmcnt(4)
	v_mfma_f32_16x16x32_bf16 v[62:65], v[188:191], v[148:151], v[62:65]
	v_mfma_f32_16x16x32_bf16 v[58:61], v[192:195], v[148:151], v[58:61]
	v_mfma_f32_16x16x32_bf16 v[54:57], v[208:211], v[148:151], v[54:57]
	v_mfma_f32_16x16x32_bf16 v[50:53], v[212:215], v[148:151], v[50:53]
	v_mfma_f32_16x16x32_bf16 v[46:49], v[188:191], v[152:155], v[46:49]
	v_mfma_f32_16x16x32_bf16 v[42:45], v[192:195], v[152:155], v[42:45]
	v_mfma_f32_16x16x32_bf16 v[38:41], v[208:211], v[152:155], v[38:41]
	v_mfma_f32_16x16x32_bf16 v[34:37], v[212:215], v[152:155], v[34:37]
	v_mfma_f32_16x16x32_bf16 v[30:33], v[188:191], v[156:159], v[30:33]
	v_mfma_f32_16x16x32_bf16 v[26:29], v[192:195], v[156:159], v[26:29]
	v_mfma_f32_16x16x32_bf16 v[22:25], v[208:211], v[156:159], v[22:25]
	v_mfma_f32_16x16x32_bf16 v[18:21], v[212:215], v[156:159], v[18:21]
	v_mfma_f32_16x16x32_bf16 v[14:17], v[188:191], v[160:163], v[14:17]
	v_mfma_f32_16x16x32_bf16 v[10:13], v[192:195], v[160:163], v[10:13]
	v_mfma_f32_16x16x32_bf16 v[6:9], v[208:211], v[160:163], v[6:9]
	v_mfma_f32_16x16x32_bf16 v[2:5], v[212:215], v[160:163], v[2:5]
	s_waitcnt lgkmcnt(0)
	v_mfma_f32_16x16x32_bf16 v[66:69], v[188:191], v[164:167], v[66:69]
	v_mfma_f32_16x16x32_bf16 v[70:73], v[192:195], v[164:167], v[70:73]
	v_mfma_f32_16x16x32_bf16 v[82:85], v[208:211], v[164:167], v[82:85]
	v_mfma_f32_16x16x32_bf16 v[88:91], v[212:215], v[164:167], v[88:91]
	v_mfma_f32_16x16x32_bf16 v[92:95], v[188:191], v[168:171], v[92:95]
	v_mfma_f32_16x16x32_bf16 v[96:99], v[192:195], v[168:171], v[96:99]
	v_mfma_f32_16x16x32_bf16 v[100:103], v[208:211], v[168:171], v[100:103]
	v_mfma_f32_16x16x32_bf16 v[106:109], v[212:215], v[168:171], v[106:109]
	v_mfma_f32_16x16x32_bf16 v[110:113], v[188:191], v[174:177], v[110:113]
	v_mfma_f32_16x16x32_bf16 v[114:117], v[192:195], v[174:177], v[114:117]
	v_mfma_f32_16x16x32_bf16 v[118:121], v[208:211], v[174:177], v[118:121]
	v_mfma_f32_16x16x32_bf16 v[122:125], v[212:215], v[174:177], v[122:125]
	v_mfma_f32_16x16x32_bf16 v[126:129], v[188:191], v[182:185], v[126:129]
	v_mfma_f32_16x16x32_bf16 v[136:139], v[192:195], v[182:185], v[136:139]
	v_mfma_f32_16x16x32_bf16 v[140:143], v[208:211], v[182:185], v[140:143]
	v_mfma_f32_16x16x32_bf16 v[144:147], v[212:215], v[182:185], v[144:147]
	s_setprio 0
	ds_read_b128 v[148:151], v80 offset:0
	ds_read_b128 v[152:155], v80 offset:2048
	ds_read_b128 v[156:159], v80 offset:4096
	ds_read_b128 v[160:163], v80 offset:6144
	ds_read_b128 v[188:191], v81 offset:32768
	ds_read_b128 v[192:195], v81 offset:34816
	ds_read_b128 v[208:211], v81 offset:36864
	ds_read_b128 v[212:215], v81 offset:38912
	ds_read_b128 v[164:167], v80 offset:16384
	ds_read_b128 v[168:171], v80 offset:18432
	ds_read_b128 v[174:177], v80 offset:20480
	ds_read_b128 v[182:185], v80 offset:22528
	s_waitcnt lgkmcnt(0)
	s_barrier
	s_add_i32 m0, s58, 0x0
	s_nop 0
	global_load_lds_dwordx4 v74, s[50:51]
	s_add_i32 m0, s58, 0x1000
	s_nop 0
	global_load_lds_dwordx4 v75, s[50:51]
	s_add_i32 m0, s58, 0x2000
	s_nop 0
	global_load_lds_dwordx4 v76, s[50:51]
	s_add_i32 m0, s58, 0x3000
	s_nop 0
	global_load_lds_dwordx4 v77, s[50:51]
	s_add_i32 m0, s58, 0x4000
	s_nop 0
	global_load_lds_dwordx4 v74, s[52:53]
	s_add_i32 m0, s58, 0x5000
	s_nop 0
	global_load_lds_dwordx4 v75, s[52:53]
	s_add_i32 m0, s58, 0x6000
	s_nop 0
	global_load_lds_dwordx4 v76, s[52:53]
	s_add_i32 m0, s58, 0x7000
	s_nop 0
	global_load_lds_dwordx4 v77, s[52:53]
	s_add_u32 s50, s50, 0x80
	s_addc_u32 s51, s51, 0
	s_add_u32 s52, s52, 0x80
	s_addc_u32 s53, s53, 0
	s_setprio 1
	v_mfma_f32_16x16x32_bf16 v[62:65], v[188:191], v[148:151], v[62:65]
	v_mfma_f32_16x16x32_bf16 v[58:61], v[192:195], v[148:151], v[58:61]
	v_mfma_f32_16x16x32_bf16 v[54:57], v[208:211], v[148:151], v[54:57]
	v_mfma_f32_16x16x32_bf16 v[50:53], v[212:215], v[148:151], v[50:53]
	v_mfma_f32_16x16x32_bf16 v[46:49], v[188:191], v[152:155], v[46:49]
	v_mfma_f32_16x16x32_bf16 v[42:45], v[192:195], v[152:155], v[42:45]
	v_mfma_f32_16x16x32_bf16 v[38:41], v[208:211], v[152:155], v[38:41]
	v_mfma_f32_16x16x32_bf16 v[34:37], v[212:215], v[152:155], v[34:37]
	v_mfma_f32_16x16x32_bf16 v[30:33], v[188:191], v[156:159], v[30:33]
	v_mfma_f32_16x16x32_bf16 v[26:29], v[192:195], v[156:159], v[26:29]
	v_mfma_f32_16x16x32_bf16 v[22:25], v[208:211], v[156:159], v[22:25]
	v_mfma_f32_16x16x32_bf16 v[18:21], v[212:215], v[156:159], v[18:21]
	v_mfma_f32_16x16x32_bf16 v[14:17], v[188:191], v[160:163], v[14:17]
	v_mfma_f32_16x16x32_bf16 v[10:13], v[192:195], v[160:163], v[10:13]
	v_mfma_f32_16x16x32_bf16 v[6:9], v[208:211], v[160:163], v[6:9]
	v_mfma_f32_16x16x32_bf16 v[2:5], v[212:215], v[160:163], v[2:5]
	v_mfma_f32_16x16x32_bf16 v[66:69], v[188:191], v[164:167], v[66:69]
	v_mfma_f32_16x16x32_bf16 v[70:73], v[192:195], v[164:167], v[70:73]
	v_mfma_f32_16x16x32_bf16 v[82:85], v[208:211], v[164:167], v[82:85]
	v_mfma_f32_16x16x32_bf16 v[88:91], v[212:215], v[164:167], v[88:91]
	v_mfma_f32_16x16x32_bf16 v[92:95], v[188:191], v[168:171], v[92:95]
	v_mfma_f32_16x16x32_bf16 v[96:99], v[192:195], v[168:171], v[96:99]
	v_mfma_f32_16x16x32_bf16 v[100:103], v[208:211], v[168:171], v[100:103]
	v_mfma_f32_16x16x32_bf16 v[106:109], v[212:215], v[168:171], v[106:109]
	v_mfma_f32_16x16x32_bf16 v[110:113], v[188:191], v[174:177], v[110:113]
	v_mfma_f32_16x16x32_bf16 v[114:117], v[192:195], v[174:177], v[114:117]
	v_mfma_f32_16x16x32_bf16 v[118:121], v[208:211], v[174:177], v[118:121]
	v_mfma_f32_16x16x32_bf16 v[122:125], v[212:215], v[174:177], v[122:125]
	v_mfma_f32_16x16x32_bf16 v[126:129], v[188:191], v[182:185], v[126:129]
	v_mfma_f32_16x16x32_bf16 v[136:139], v[192:195], v[182:185], v[136:139]
	v_mfma_f32_16x16x32_bf16 v[140:143], v[208:211], v[182:185], v[140:143]
	v_mfma_f32_16x16x32_bf16 v[144:147], v[212:215], v[182:185], v[144:147]
	s_setprio 0
	s_waitcnt vmcnt(0)
	s_barrier
	ds_read_b128 v[148:151], v78 offset:0
	ds_read_b128 v[152:155], v78 offset:2048
	ds_read_b128 v[156:159], v78 offset:4096
	ds_read_b128 v[160:163], v78 offset:6144
	ds_read_b128 v[188:191], v79 offset:49152
	ds_read_b128 v[192:195], v79 offset:51200
	ds_read_b128 v[208:211], v79 offset:53248
	ds_read_b128 v[212:215], v79 offset:55296
	ds_read_b128 v[164:167], v78 offset:16384
	ds_read_b128 v[168:171], v78 offset:18432
	ds_read_b128 v[174:177], v78 offset:20480
	ds_read_b128 v[182:185], v78 offset:22528
	s_setprio 1
	s_waitcnt lgkmcnt(4)
	v_mfma_f32_16x16x32_bf16 v[62:65], v[188:191], v[148:151], v[62:65]
	v_mfma_f32_16x16x32_bf16 v[58:61], v[192:195], v[148:151], v[58:61]
	v_mfma_f32_16x16x32_bf16 v[54:57], v[208:211], v[148:151], v[54:57]
	v_mfma_f32_16x16x32_bf16 v[50:53], v[212:215], v[148:151], v[50:53]
	v_mfma_f32_16x16x32_bf16 v[46:49], v[188:191], v[152:155], v[46:49]
	v_mfma_f32_16x16x32_bf16 v[42:45], v[192:195], v[152:155], v[42:45]
	v_mfma_f32_16x16x32_bf16 v[38:41], v[208:211], v[152:155], v[38:41]
	v_mfma_f32_16x16x32_bf16 v[34:37], v[212:215], v[152:155], v[34:37]
	v_mfma_f32_16x16x32_bf16 v[30:33], v[188:191], v[156:159], v[30:33]
	v_mfma_f32_16x16x32_bf16 v[26:29], v[192:195], v[156:159], v[26:29]
	v_mfma_f32_16x16x32_bf16 v[22:25], v[208:211], v[156:159], v[22:25]
	v_mfma_f32_16x16x32_bf16 v[18:21], v[212:215], v[156:159], v[18:21]
	v_mfma_f32_16x16x32_bf16 v[14:17], v[188:191], v[160:163], v[14:17]
	v_mfma_f32_16x16x32_bf16 v[10:13], v[192:195], v[160:163], v[10:13]
	v_mfma_f32_16x16x32_bf16 v[6:9], v[208:211], v[160:163], v[6:9]
	v_mfma_f32_16x16x32_bf16 v[2:5], v[212:215], v[160:163], v[2:5]
	s_waitcnt lgkmcnt(0)
	v_mfma_f32_16x16x32_bf16 v[66:69], v[188:191], v[164:167], v[66:69]
	v_mfma_f32_16x16x32_bf16 v[70:73], v[192:195], v[164:167], v[70:73]
	v_mfma_f32_16x16x32_bf16 v[82:85], v[208:211], v[164:167], v[82:85]
	v_mfma_f32_16x16x32_bf16 v[88:91], v[212:215], v[164:167], v[88:91]
	v_mfma_f32_16x16x32_bf16 v[92:95], v[188:191], v[168:171], v[92:95]
	v_mfma_f32_16x16x32_bf16 v[96:99], v[192:195], v[168:171], v[96:99]
	v_mfma_f32_16x16x32_bf16 v[100:103], v[208:211], v[168:171], v[100:103]
	v_mfma_f32_16x16x32_bf16 v[106:109], v[212:215], v[168:171], v[106:109]
	v_mfma_f32_16x16x32_bf16 v[110:113], v[188:191], v[174:177], v[110:113]
	v_mfma_f32_16x16x32_bf16 v[114:117], v[192:195], v[174:177], v[114:117]
	v_mfma_f32_16x16x32_bf16 v[118:121], v[208:211], v[174:177], v[118:121]
	v_mfma_f32_16x16x32_bf16 v[122:125], v[212:215], v[174:177], v[122:125]
	v_mfma_f32_16x16x32_bf16 v[126:129], v[188:191], v[182:185], v[126:129]
	v_mfma_f32_16x16x32_bf16 v[136:139], v[192:195], v[182:185], v[136:139]
	v_mfma_f32_16x16x32_bf16 v[140:143], v[208:211], v[182:185], v[140:143]
	v_mfma_f32_16x16x32_bf16 v[144:147], v[212:215], v[182:185], v[144:147]
	s_setprio 0
	ds_read_b128 v[148:151], v80 offset:0
	ds_read_b128 v[152:155], v80 offset:2048
	ds_read_b128 v[156:159], v80 offset:4096
	ds_read_b128 v[160:163], v80 offset:6144
	ds_read_b128 v[188:191], v81 offset:49152
	ds_read_b128 v[192:195], v81 offset:51200
	ds_read_b128 v[208:211], v81 offset:53248
	ds_read_b128 v[212:215], v81 offset:55296
	ds_read_b128 v[164:167], v80 offset:16384
	ds_read_b128 v[168:171], v80 offset:18432
	ds_read_b128 v[174:177], v80 offset:20480
	ds_read_b128 v[182:185], v80 offset:22528
	s_setprio 1
	s_waitcnt lgkmcnt(4)
	v_mfma_f32_16x16x32_bf16 v[62:65], v[188:191], v[148:151], v[62:65]
	v_mfma_f32_16x16x32_bf16 v[58:61], v[192:195], v[148:151], v[58:61]
	v_mfma_f32_16x16x32_bf16 v[54:57], v[208:211], v[148:151], v[54:57]
	v_mfma_f32_16x16x32_bf16 v[50:53], v[212:215], v[148:151], v[50:53]
	v_mfma_f32_16x16x32_bf16 v[46:49], v[188:191], v[152:155], v[46:49]
	v_mfma_f32_16x16x32_bf16 v[42:45], v[192:195], v[152:155], v[42:45]
	v_mfma_f32_16x16x32_bf16 v[38:41], v[208:211], v[152:155], v[38:41]
	v_mfma_f32_16x16x32_bf16 v[34:37], v[212:215], v[152:155], v[34:37]
	v_mfma_f32_16x16x32_bf16 v[30:33], v[188:191], v[156:159], v[30:33]
	v_mfma_f32_16x16x32_bf16 v[26:29], v[192:195], v[156:159], v[26:29]
	v_mfma_f32_16x16x32_bf16 v[22:25], v[208:211], v[156:159], v[22:25]
	v_mfma_f32_16x16x32_bf16 v[18:21], v[212:215], v[156:159], v[18:21]
	v_mfma_f32_16x16x32_bf16 v[14:17], v[188:191], v[160:163], v[14:17]
	v_mfma_f32_16x16x32_bf16 v[10:13], v[192:195], v[160:163], v[10:13]
	v_mfma_f32_16x16x32_bf16 v[6:9], v[208:211], v[160:163], v[6:9]
	v_mfma_f32_16x16x32_bf16 v[2:5], v[212:215], v[160:163], v[2:5]
	s_waitcnt lgkmcnt(0)
	v_mfma_f32_16x16x32_bf16 v[66:69], v[188:191], v[164:167], v[66:69]
	v_mfma_f32_16x16x32_bf16 v[70:73], v[192:195], v[164:167], v[70:73]
	v_mfma_f32_16x16x32_bf16 v[82:85], v[208:211], v[164:167], v[82:85]
	v_mfma_f32_16x16x32_bf16 v[88:91], v[212:215], v[164:167], v[88:91]
	v_mfma_f32_16x16x32_bf16 v[92:95], v[188:191], v[168:171], v[92:95]
	v_mfma_f32_16x16x32_bf16 v[96:99], v[192:195], v[168:171], v[96:99]
	v_mfma_f32_16x16x32_bf16 v[100:103], v[208:211], v[168:171], v[100:103]
	v_mfma_f32_16x16x32_bf16 v[106:109], v[212:215], v[168:171], v[106:109]
	v_mfma_f32_16x16x32_bf16 v[110:113], v[188:191], v[174:177], v[110:113]
	v_mfma_f32_16x16x32_bf16 v[114:117], v[192:195], v[174:177], v[114:117]
	v_mfma_f32_16x16x32_bf16 v[118:121], v[208:211], v[174:177], v[118:121]
	v_mfma_f32_16x16x32_bf16 v[122:125], v[212:215], v[174:177], v[122:125]
	v_mfma_f32_16x16x32_bf16 v[126:129], v[188:191], v[182:185], v[126:129]
	v_mfma_f32_16x16x32_bf16 v[136:139], v[192:195], v[182:185], v[136:139]
	v_mfma_f32_16x16x32_bf16 v[140:143], v[208:211], v[182:185], v[140:143]
	v_mfma_f32_16x16x32_bf16 v[144:147], v[212:215], v[182:185], v[144:147]
	s_setprio 0
	s_nop 7
	s_nop 7
	s_nop 7
	v_mov_b32_e32 v148, v66
	v_mov_b32_e32 v149, v67
	v_mov_b32_e32 v150, v68
	v_mov_b32_e32 v151, v69
	v_mov_b32_e32 v152, v70
	v_mov_b32_e32 v153, v71
	v_mov_b32_e32 v154, v72
	v_mov_b32_e32 v155, v73
	v_mov_b32_e32 v156, v82
	v_mov_b32_e32 v157, v83
	v_mov_b32_e32 v158, v84
	v_mov_b32_e32 v159, v85
	v_mov_b32_e32 v160, v88
	v_mov_b32_e32 v161, v89
	v_mov_b32_e32 v162, v90
	v_mov_b32_e32 v163, v91
	v_mov_b32_e32 v164, v92
	v_mov_b32_e32 v165, v93
	v_mov_b32_e32 v166, v94
	v_mov_b32_e32 v167, v95
	v_mov_b32_e32 v168, v96
	v_mov_b32_e32 v169, v97
	v_mov_b32_e32 v170, v98
	v_mov_b32_e32 v171, v99
	v_mov_b32_e32 v174, v100
	v_mov_b32_e32 v175, v101
	v_mov_b32_e32 v176, v102
	v_mov_b32_e32 v177, v103
	v_mov_b32_e32 v182, v106
	v_mov_b32_e32 v183, v107
	v_mov_b32_e32 v184, v108
	v_mov_b32_e32 v185, v109
	v_mov_b32_e32 v188, v110
	v_mov_b32_e32 v189, v111
	v_mov_b32_e32 v190, v112
	v_mov_b32_e32 v191, v113
	v_mov_b32_e32 v192, v114
	v_mov_b32_e32 v193, v115
	v_mov_b32_e32 v194, v116
	v_mov_b32_e32 v195, v117
	v_mov_b32_e32 v208, v118
	v_mov_b32_e32 v209, v119
	v_mov_b32_e32 v210, v120
	v_mov_b32_e32 v211, v121
	v_mov_b32_e32 v212, v122
	v_mov_b32_e32 v213, v123
	v_mov_b32_e32 v214, v124
	v_mov_b32_e32 v215, v125
	v_mov_b32_e32 v216, v126
	v_mov_b32_e32 v217, v127
	v_mov_b32_e32 v218, v128
	v_mov_b32_e32 v219, v129
	v_mov_b32_e32 v220, v136
	v_mov_b32_e32 v221, v137
	v_mov_b32_e32 v222, v138
	v_mov_b32_e32 v223, v139
	v_mov_b32_e32 v242, v140
	v_mov_b32_e32 v243, v141
	v_mov_b32_e32 v244, v142
	v_mov_b32_e32 v245, v143
	v_mov_b32_e32 v199, v144
	v_mov_b32_e32 v206, v145
	v_mov_b32_e32 v207, v146
	v_mov_b32_e32 v226, v147
	s_add_i32 s48, s48, 1
	s_mov_b32 s65, 0
	v_readlane_b32 s2, v249, 0
	s_nop 0
	s_and_b32 s3, s2, 7
	s_lshr_b32 s2, s2, 3
	s_cmp_lt_u32 s2, 40
	s_cselect_b32 s38, 7, 6
	s_cmp_lt_u32 s48, s38
	s_cbranch_scc0 .Lg2_c1_extra
	s_lshl_b32 s20, s48, 6
	s_add_i32 s20, s20, s2
	s_cmp_ge_u32 s20, 0xd4
	s_cselect_b32 s21, 1, 0
	s_mul_i32 s60, s21, 0xd4
	s_sub_i32 s20, s20, s60
	s_lshr_b32 s61, s20, 2
	s_and_b32 s20, s20, 3
	s_lshl_b32 s21, s21, 3
	s_add_i32 s20, s20, s21
	s_lshl_b32 s20, s20, 3
	s_add_i32 s60, s20, s3
	s_add_i32 s64, s60, 32
	s_branch .Lg2_c1_have
.Lg2_c1_extra:
	s_cmp_eq_u32 s48, s38
	s_cbranch_scc0 .Lg2_nopf
	s_cmp_lt_u32 s2, 40
	s_cbranch_scc1 .Lg2_nopf
	s_sub_i32 s20, s2, 40
	s_lshl_b32 s20, s20, 3
	s_add_i32 s61, s20, s3
	s_cmp_lt_u32 s61, 53
	s_cbranch_scc0 .Lg2_nopf
	s_movk_i32 s60, 0x80
	s_movk_i32 s64, 0x81
.Lg2_c1_have:
	s_mov_b32 s65, 2
	s_lshl_b32 s2, s60, 18
	s_add_u32 s50, s12, s2
	s_addc_u32 s51, s13, 0
	s_lshl_b32 s2, s64, 18
	s_add_u32 s52, s12, s2
	s_addc_u32 s53, s13, 0
	s_lshl_b32 s2, s61, 18
	s_add_u32 s56, s34, s2
	s_addc_u32 s57, s35, 0
	s_barrier
	s_add_i32 m0, s58, 0x0
	s_nop 0
	global_load_lds_dwordx4 v74, s[50:51]
	s_add_i32 m0, s58, 0x1000
	s_nop 0
	global_load_lds_dwordx4 v75, s[50:51]
	s_add_i32 m0, s58, 0x2000
	s_nop 0
	global_load_lds_dwordx4 v76, s[50:51]
	s_add_i32 m0, s58, 0x3000
	s_nop 0
	global_load_lds_dwordx4 v77, s[50:51]
	s_add_i32 m0, s58, 0x4000
	s_nop 0
	global_load_lds_dwordx4 v74, s[52:53]
	s_add_i32 m0, s58, 0x5000
	s_nop 0
	global_load_lds_dwordx4 v75, s[52:53]
	s_add_i32 m0, s58, 0x6000
	s_nop 0
	global_load_lds_dwordx4 v76, s[52:53]
	s_add_i32 m0, s58, 0x7000
	s_nop 0
	global_load_lds_dwordx4 v77, s[52:53]
	s_add_u32 s50, s50, 0x80
	s_addc_u32 s51, s51, 0
	s_add_u32 s52, s52, 0x80
	s_addc_u32 s53, s53, 0
	s_add_i32 m0, s58, 0x8000
	s_nop 0
	global_load_lds_dwordx4 v74, s[56:57]
	s_add_i32 m0, s58, 0x9000
	s_nop 0
	global_load_lds_dwordx4 v75, s[56:57]
	s_add_i32 m0, s58, 0xa000
	s_nop 0
	global_load_lds_dwordx4 v76, s[56:57]
	s_add_i32 m0, s58, 0xb000
	s_nop 0
	global_load_lds_dwordx4 v77, s[56:57]
	s_add_u32 s56, s56, 0x80
	s_addc_u32 s57, s57, 0
.Lg2_nopf:
	s_mov_b32 s32, 1
	s_branch .LBB0_222

.Lg2_next:
	s_cmp_eq_u32 s65, 0
	s_cbranch_scc1 .Lg2_done
	s_mov_b32 s0, s60
	s_mov_b32 s37, s61
	s_mov_b32 s49, s64
	s_branch .Lg2_setup

.LBB0_2352:
	v_and_b32_e32 v2, 15, v0
	v_ashrrev_i32_e32 v3, 1, v0
	s_movk_i32 s8, 0xffc0
	s_waitcnt vmcnt(2)
	v_and_or_b32 v74, v3, s8, v2
	v_lshrrev_b32_e32 v2, 1, v0
	v_lshrrev_b32_e32 v0, 2, v0
	s_and_b32 s17, s2, 7
	v_and_b32_e32 v0, 12, v0
	v_and_or_b32 v75, v2, 32, v0
	v_cvt_f32_ubyte0_e32 v0, s17
	v_rcp_iflag_f32_e32 v0, v0
	s_lshr_b32 s16, s2, 3
	s_cmp_lt_i32 s12, 0
	s_cselect_b64 s[2:3], -1, 0
	v_mul_f32_e32 v0, 0x4f7ffffe, v0
	v_cvt_u32_f32_e32 v0, v0
	s_sub_i32 s8, 0, s17
	s_load_dwordx2 s[4:5], s[0:1], 0x108
	s_load_dwordx2 s[6:7], s[0:1], 0x138
	v_readfirstlane_b32 s9, v0
	s_mul_i32 s8, s8, s9
	s_mul_hi_u32 s8, s9, s8
	s_add_i32 s18, s9, s8
	v_readlane_b32 s8, v249, 52
	v_readlane_b32 s9, v249, 53
	s_mov_b32 s10, s8
	s_mul_i32 s9, s10, 0xb00000
	s_mul_hi_u32 s8, s8, 0xb00000
	s_waitcnt lgkmcnt(0)
	s_add_u32 s19, s4, s9
	s_addc_u32 s20, s5, s8
	s_waitcnt vmcnt(0)
	s_mov_b32 s32, 0
	v_readlane_b32 s30, v249, 1
	s_nop 0
	s_cmpk_lg_u32 s30, 0x200
	s_cbranch_scc1 .LBB0_2354
	s_mov_b32 s48, 0
	v_readlane_b32 s30, v249, 0
	s_nop 0
	s_and_b32 s31, s30, 7
	s_lshr_b32 s30, s30, 3
	s_cmp_lt_u32 s30, 32
	s_cselect_b32 s35, 6, 5
	s_cmp_lt_u32 s48, s35
	s_cbranch_scc0 .Lf2_c0_extra
	s_lshl_b32 s33, s48, 6
	s_add_i32 s33, s33, s30
	s_cmp_ge_u32 s33, 0xb0
	s_cselect_b32 s34, 1, 0
	s_mul_i32 s8, s34, 0xb0
	s_sub_i32 s33, s33, s8
	s_lshr_b32 s21, s33, 2
	s_and_b32 s33, s33, 3
	s_lshl_b32 s34, s34, 3
	s_add_i32 s33, s33, s34
	s_lshl_b32 s33, s33, 3
	s_add_i32 s8, s33, s31
	s_add_i32 s49, s8, 32
	s_branch .Lf2_c0_have

.Lf2_c0_have:
	s_mov_b32 s39, 1
.Lf2_setup:
	v_and_b32_e32 v70, 7, v196
	v_bfe_u32 v71, v196, 4, 2
	v_bfe_u32 v72, v196, 6, 1
	v_lshl_or_b32 v73, v72, 2, v71
	v_xor_b32_e32 v70, v70, v73
	v_lshrrev_b32_e32 v73, 3, v196
	v_lshlrev_b32_e32 v73, 11, v73
	v_lshl_or_b32 v76, v70, 4, v73
	v_add_u32_e32 v77, 0x10000, v76
	v_add_u32_e32 v78, 0x20000, v76
	v_add_u32_e32 v79, 0x30000, v76
	v_and_b32_e32 v70, 15, v196
	v_bfe_u32 v73, v196, 1, 3
	v_xor_b32_e32 v73, v71, v73
	v_lshlrev_b32_e32 v73, 4, v73
	v_xor_b32_e32 v82, 64, v73
	v_lshlrev_b32_e32 v70, 7, v70
	v_lshrrev_b32_e32 v83, 7, v196
	v_lshl_or_b32 v83, v83, 13, v70
	v_lshl_or_b32 v84, v72, 13, v70
	v_add_u32_e32 v80, v83, v73
	v_add_u32_e32 v81, v83, v82
	v_add_u32_e32 v144, v84, v73
	v_add_u32_e32 v145, v84, v82
	v_readfirstlane_b32 s64, v196
	s_lshr_b32 s64, s64, 6
	s_lshl_b32 s64, s64, 10
	s_cmp_eq_u32 s39, 2
	s_cbranch_scc1 .Lf2_loop
	s_lshl_b32 s30, s8, 18
	s_add_u32 s50, s6, s30
	s_addc_u32 s51, s7, 0
	s_lshl_b32 s30, s49, 18
	s_add_u32 s52, s6, s30
	s_addc_u32 s53, s7, 0
	s_lshl_b32 s30, s21, 18
	s_add_u32 s58, s19, s30
	s_addc_u32 s59, s20, 0
	s_barrier
	s_add_i32 m0, s64, 0x0
	s_nop 0
	global_load_lds_dwordx4 v76, s[50:51]
	s_add_i32 m0, s64, 0x1000
	s_nop 0
	global_load_lds_dwordx4 v77, s[50:51]
	s_add_i32 m0, s64, 0x2000
	s_nop 0
	global_load_lds_dwordx4 v78, s[50:51]
	s_add_i32 m0, s64, 0x3000
	s_nop 0
	global_load_lds_dwordx4 v79, s[50:51]
	s_add_i32 m0, s64, 0x4000
	s_nop 0
	global_load_lds_dwordx4 v76, s[52:53]
	s_add_i32 m0, s64, 0x5000
	s_nop 0
	global_load_lds_dwordx4 v77, s[52:53]
	s_add_i32 m0, s64, 0x6000
	s_nop 0
	global_load_lds_dwordx4 v78, s[52:53]
	s_add_i32 m0, s64, 0x7000
	s_nop 0
	global_load_lds_dwordx4 v79, s[52:53]
	s_add_u32 s50, s50, 0x80
	s_addc_u32 s51, s51, 0
	s_add_u32 s52, s52, 0x80
	s_addc_u32 s53, s53, 0
	s_add_i32 m0, s64, 0x8000
	s_nop 0
	global_load_lds_dwordx4 v76, s[58:59]
	s_add_i32 m0, s64, 0x9000
	s_nop 0
	global_load_lds_dwordx4 v77, s[58:59]
	s_add_i32 m0, s64, 0xa000
	s_nop 0
	global_load_lds_dwordx4 v78, s[58:59]
	s_add_i32 m0, s64, 0xb000
	s_nop 0
	global_load_lds_dwordx4 v79, s[58:59]
	s_add_u32 s58, s58, 0x80
	s_addc_u32 s59, s59, 0
.Lf2_loop:
	v_mov_b64_e32 v[62:63], 0
	v_mov_b64_e32 v[64:65], 0
	v_mov_b64_e32 v[54:55], 0
	v_mov_b64_e32 v[56:57], 0
	v_mov_b64_e32 v[58:59], 0
	v_mov_b64_e32 v[60:61], 0
	v_mov_b64_e32 v[50:51], 0
	v_mov_b64_e32 v[52:53], 0
	v_mov_b64_e32 v[46:47], 0
	v_mov_b64_e32 v[48:49], 0
	v_mov_b64_e32 v[38:39], 0
	v_mov_b64_e32 v[40:41], 0
	v_mov_b64_e32 v[42:43], 0
	v_mov_b64_e32 v[44:45], 0
	v_mov_b64_e32 v[34:35], 0
	v_mov_b64_e32 v[36:37], 0
	v_mov_b64_e32 v[30:31], 0
	v_mov_b64_e32 v[32:33], 0
	v_mov_b64_e32 v[22:23], 0
	v_mov_b64_e32 v[24:25], 0
	v_mov_b64_e32 v[26:27], 0
	v_mov_b64_e32 v[28:29], 0
	v_mov_b64_e32 v[18:19], 0
	v_mov_b64_e32 v[20:21], 0
	v_mov_b64_e32 v[14:15], 0
	v_mov_b64_e32 v[16:17], 0
	v_mov_b64_e32 v[6:7], 0
	v_mov_b64_e32 v[8:9], 0
	v_mov_b64_e32 v[10:11], 0
	v_mov_b64_e32 v[12:13], 0
	v_mov_b64_e32 v[2:3], 0
	v_mov_b64_e32 v[4:5], 0
	v_mov_b64_e32 v[66:67], 0
	v_mov_b64_e32 v[68:69], 0
	v_mov_b64_e32 v[70:71], 0
	v_mov_b64_e32 v[72:73], 0
	v_mov_b64_e32 v[82:83], 0
	v_mov_b64_e32 v[84:85], 0
	v_mov_b64_e32 v[86:87], 0
	v_mov_b64_e32 v[88:89], 0
	v_mov_b64_e32 v[90:91], 0
	v_mov_b64_e32 v[92:93], 0
	v_mov_b64_e32 v[94:95], 0
	v_mov_b64_e32 v[96:97], 0
	v_mov_b64_e32 v[98:99], 0
	v_mov_b64_e32 v[100:101], 0
	v_mov_b64_e32 v[102:103], 0
	v_mov_b64_e32 v[104:105], 0
	v_mov_b64_e32 v[106:107], 0
	v_mov_b64_e32 v[108:109], 0
	v_mov_b64_e32 v[110:111], 0
	v_mov_b64_e32 v[112:113], 0
	v_mov_b64_e32 v[114:115], 0
	v_mov_b64_e32 v[116:117], 0
	v_mov_b64_e32 v[118:119], 0
	v_mov_b64_e32 v[120:121], 0
	v_mov_b64_e32 v[122:123], 0
	v_mov_b64_e32 v[124:125], 0
	v_mov_b64_e32 v[126:127], 0
	v_mov_b64_e32 v[128:129], 0
	v_mov_b64_e32 v[136:137], 0
	v_mov_b64_e32 v[138:139], 0
	v_mov_b64_e32 v[140:141], 0
	v_mov_b64_e32 v[142:143], 0
	s_movk_i32 s65, 7
.Lf2_k:
	s_waitcnt vmcnt(0)
	s_barrier
	s_add_i32 m0, s64, 0xc000
	s_nop 0
	global_load_lds_dwordx4 v76, s[58:59]
	s_add_i32 m0, s64, 0xd000
	s_nop 0
	global_load_lds_dwordx4 v77, s[58:59]
	s_add_i32 m0, s64, 0xe000
	s_nop 0
	global_load_lds_dwordx4 v78, s[58:59]
	s_add_i32 m0, s64, 0xf000
	s_nop 0
	global_load_lds_dwordx4 v79, s[58:59]
	s_add_u32 s58, s58, 0x80
	s_addc_u32 s59, s59, 0
	ds_read_b128 v[148:151], v80 offset:0
	ds_read_b128 v[152:155], v80 offset:2048
	ds_read_b128 v[156:159], v80 offset:4096
	ds_read_b128 v[160:163], v80 offset:6144
	ds_read_b128 v[188:191], v144 offset:32768
	ds_read_b128 v[192:195], v144 offset:34816
	ds_read_b128 v[208:211], v144 offset:36864
	ds_read_b128 v[212:215], v144 offset:38912
	ds_read_b128 v[164:167], v80 offset:16384
	ds_read_b128 v[168:171], v80 offset:18432
	ds_read_b128 v[174:177], v80 offset:20480
	ds_read_b128 v[182:185], v80 offset:22528
	s_setprio 1
	s_waitcnt lgkmcnt(4)
	v_mfma_f32_16x16x32_bf16 v[62:65], v[188:191], v[148:151], v[62:65]
	v_mfma_f32_16x16x32_bf16 v[54:57], v[192:195], v[148:151], v[54:57]
	v_mfma_f32_16x16x32_bf16 v[58:61], v[208:211], v[148:151], v[58:61]
	v_mfma_f32_16x16x32_bf16 v[50:53], v[212:215], v[148:151], v[50:53]
	v_mfma_f32_16x16x32_bf16 v[46:49], v[188:191], v[152:155], v[46:49]
	v_mfma_f32_16x16x32_bf16 v[38:41], v[192:195], v[152:155], v[38:41]
	v_mfma_f32_16x16x32_bf16 v[42:45], v[208:211], v[152:155], v[42:45]
	v_mfma_f32_16x16x32_bf16 v[34:37], v[212:215], v[152:155], v[34:37]
	v_mfma_f32_16x16x32_bf16 v[30:33], v[188:191], v[156:159], v[30:33]
	v_mfma_f32_16x16x32_bf16 v[22:25], v[192:195], v[156:159], v[22:25]
	v_mfma_f32_16x16x32_bf16 v[26:29], v[208:211], v[156:159], v[26:29]
	v_mfma_f32_16x16x32_bf16 v[18:21], v[212:215], v[156:159], v[18:21]
	v_mfma_f32_16x16x32_bf16 v[14:17], v[188:191], v[160:163], v[14:17]
	v_mfma_f32_16x16x32_bf16 v[6:9], v[192:195], v[160:163], v[6:9]
	v_mfma_f32_16x16x32_bf16 v[10:13], v[208:211], v[160:163], v[10:13]
	v_mfma_f32_16x16x32_bf16 v[2:5], v[212:215], v[160:163], v[2:5]
	s_waitcnt lgkmcnt(0)
	v_mfma_f32_16x16x32_bf16 v[66:69], v[188:191], v[164:167], v[66:69]
	v_mfma_f32_16x16x32_bf16 v[70:73], v[192:195], v[164:167], v[70:73]
	v_mfma_f32_16x16x32_bf16 v[82:85], v[208:211], v[164:167], v[82:85]
	v_mfma_f32_16x16x32_bf16 v[86:89], v[212:215], v[164:167], v[86:89]
	v_mfma_f32_16x16x32_bf16 v[90:93], v[188:191], v[168:171], v[90:93]
	v_mfma_f32_16x16x32_bf16 v[94:97], v[192:195], v[168:171], v[94:97]
	v_mfma_f32_16x16x32_bf16 v[98:101], v[208:211], v[168:171], v[98:101]
	v_mfma_f32_16x16x32_bf16 v[102:105], v[212:215], v[168:171], v[102:105]
	v_mfma_f32_16x16x32_bf16 v[106:109], v[188:191], v[174:177], v[106:109]
	v_mfma_f32_16x16x32_bf16 v[110:113], v[192:195], v[174:177], v[110:113]
	v_mfma_f32_16x16x32_bf16 v[114:117], v[208:211], v[174:177], v[114:117]
	v_mfma_f32_16x16x32_bf16 v[118:121], v[212:215], v[174:177], v[118:121]
	v_mfma_f32_16x16x32_bf16 v[122:125], v[188:191], v[182:185], v[122:125]
	v_mfma_f32_16x16x32_bf16 v[126:129], v[192:195], v[182:185], v[126:129]
	v_mfma_f32_16x16x32_bf16 v[136:139], v[208:211], v[182:185], v[136:139]
	v_mfma_f32_16x16x32_bf16 v[140:143], v[212:215], v[182:185], v[140:143]
	s_setprio 0
	ds_read_b128 v[148:151], v81 offset:0
	ds_read_b128 v[152:155], v81 offset:2048
	ds_read_b128 v[156:159], v81 offset:4096
	ds_read_b128 v[160:163], v81 offset:6144
	ds_read_b128 v[188:191], v145 offset:32768
	ds_read_b128 v[192:195], v145 offset:34816
	ds_read_b128 v[208:211], v145 offset:36864
	ds_read_b128 v[212:215], v145 offset:38912
	ds_read_b128 v[164:167], v81 offset:16384
	ds_read_b128 v[168:171], v81 offset:18432
	ds_read_b128 v[174:177], v81 offset:20480
	ds_read_b128 v[182:185], v81 offset:22528
	s_waitcnt lgkmcnt(0)
	s_barrier
	s_add_i32 m0, s64, 0x0
	s_nop 0
	global_load_lds_dwordx4 v76, s[50:51]
	s_add_i32 m0, s64, 0x1000
	s_nop 0
	global_load_lds_dwordx4 v77, s[50:51]
	s_add_i32 m0, s64, 0x2000
	s_nop 0
	global_load_lds_dwordx4 v78, s[50:51]
	s_add_i32 m0, s64, 0x3000
	s_nop 0
	global_load_lds_dwordx4 v79, s[50:51]
	s_add_i32 m0, s64, 0x4000
	s_nop 0
	global_load_lds_dwordx4 v76, s[52:53]
	s_add_i32 m0, s64, 0x5000
	s_nop 0
	global_load_lds_dwordx4 v77, s[52:53]
	s_add_i32 m0, s64, 0x6000
	s_nop 0
	global_load_lds_dwordx4 v78, s[52:53]
	s_add_i32 m0, s64, 0x7000
	s_nop 0
	global_load_lds_dwordx4 v79, s[52:53]
	s_add_u32 s50, s50, 0x80
	s_addc_u32 s51, s51, 0
	s_add_u32 s52, s52, 0x80
	s_addc_u32 s53, s53, 0
	s_setprio 1
	v_mfma_f32_16x16x32_bf16 v[62:65], v[188:191], v[148:151], v[62:65]
	v_mfma_f32_16x16x32_bf16 v[54:57], v[192:195], v[148:151], v[54:57]
	v_mfma_f32_16x16x32_bf16 v[58:61], v[208:211], v[148:151], v[58:61]
	v_mfma_f32_16x16x32_bf16 v[50:53], v[212:215], v[148:151], v[50:53]
	v_mfma_f32_16x16x32_bf16 v[46:49], v[188:191], v[152:155], v[46:49]
	v_mfma_f32_16x16x32_bf16 v[38:41], v[192:195], v[152:155], v[38:41]
	v_mfma_f32_16x16x32_bf16 v[42:45], v[208:211], v[152:155], v[42:45]
	v_mfma_f32_16x16x32_bf16 v[34:37], v[212:215], v[152:155], v[34:37]
	v_mfma_f32_16x16x32_bf16 v[30:33], v[188:191], v[156:159], v[30:33]
	v_mfma_f32_16x16x32_bf16 v[22:25], v[192:195], v[156:159], v[22:25]
	v_mfma_f32_16x16x32_bf16 v[26:29], v[208:211], v[156:159], v[26:29]
	v_mfma_f32_16x16x32_bf16 v[18:21], v[212:215], v[156:159], v[18:21]
	v_mfma_f32_16x16x32_bf16 v[14:17], v[188:191], v[160:163], v[14:17]
	v_mfma_f32_16x16x32_bf16 v[6:9], v[192:195], v[160:163], v[6:9]
	v_mfma_f32_16x16x32_bf16 v[10:13], v[208:211], v[160:163], v[10:13]
	v_mfma_f32_16x16x32_bf16 v[2:5], v[212:215], v[160:163], v[2:5]
	v_mfma_f32_16x16x32_bf16 v[66:69], v[188:191], v[164:167], v[66:69]
	v_mfma_f32_16x16x32_bf16 v[70:73], v[192:195], v[164:167], v[70:73]
	v_mfma_f32_16x16x32_bf16 v[82:85], v[208:211], v[164:167], v[82:85]
	v_mfma_f32_16x16x32_bf16 v[86:89], v[212:215], v[164:167], v[86:89]
	v_mfma_f32_16x16x32_bf16 v[90:93], v[188:191], v[168:171], v[90:93]
	v_mfma_f32_16x16x32_bf16 v[94:97], v[192:195], v[168:171], v[94:97]
	v_mfma_f32_16x16x32_bf16 v[98:101], v[208:211], v[168:171], v[98:101]
	v_mfma_f32_16x16x32_bf16 v[102:105], v[212:215], v[168:171], v[102:105]
	v_mfma_f32_16x16x32_bf16 v[106:109], v[188:191], v[174:177], v[106:109]
	v_mfma_f32_16x16x32_bf16 v[110:113], v[192:195], v[174:177], v[110:113]
	v_mfma_f32_16x16x32_bf16 v[114:117], v[208:211], v[174:177], v[114:117]
	v_mfma_f32_16x16x32_bf16 v[118:121], v[212:215], v[174:177], v[118:121]
	v_mfma_f32_16x16x32_bf16 v[122:125], v[188:191], v[182:185], v[122:125]
	v_mfma_f32_16x16x32_bf16 v[126:129], v[192:195], v[182:185], v[126:129]
	v_mfma_f32_16x16x32_bf16 v[136:139], v[208:211], v[182:185], v[136:139]
	v_mfma_f32_16x16x32_bf16 v[140:143], v[212:215], v[182:185], v[140:143]
	s_setprio 0
	s_waitcnt vmcnt(0)
	s_barrier
	s_add_i32 m0, s64, 0x8000
	s_nop 0
	global_load_lds_dwordx4 v76, s[58:59]
	s_add_i32 m0, s64, 0x9000
	s_nop 0
	global_load_lds_dwordx4 v77, s[58:59]
	s_add_i32 m0, s64, 0xa000
	s_nop 0
	global_load_lds_dwordx4 v78, s[58:59]
	s_add_i32 m0, s64, 0xb000
	s_nop 0
	global_load_lds_dwordx4 v79, s[58:59]
	s_add_u32 s58, s58, 0x80
	s_addc_u32 s59, s59, 0
	ds_read_b128 v[148:151], v80 offset:0
	ds_read_b128 v[152:155], v80 offset:2048
	ds_read_b128 v[156:159], v80 offset:4096
	ds_read_b128 v[160:163], v80 offset:6144
	ds_read_b128 v[188:191], v144 offset:49152
	ds_read_b128 v[192:195], v144 offset:51200
	ds_read_b128 v[208:211], v144 offset:53248
	ds_read_b128 v[212:215], v144 offset:55296
	ds_read_b128 v[164:167], v80 offset:16384
	ds_read_b128 v[168:171], v80 offset:18432
	ds_read_b128 v[174:177], v80 offset:20480
	ds_read_b128 v[182:185], v80 offset:22528
	s_setprio 1
	s_waitcnt lgkmcnt(4)
	v_mfma_f32_16x16x32_bf16 v[62:65], v[188:191], v[148:151], v[62:65]
	v_mfma_f32_16x16x32_bf16 v[54:57], v[192:195], v[148:151], v[54:57]
	v_mfma_f32_16x16x32_bf16 v[58:61], v[208:211], v[148:151], v[58:61]
	v_mfma_f32_16x16x32_bf16 v[50:53], v[212:215], v[148:151], v[50:53]
	v_mfma_f32_16x16x32_bf16 v[46:49], v[188:191], v[152:155], v[46:49]
	v_mfma_f32_16x16x32_bf16 v[38:41], v[192:195], v[152:155], v[38:41]
	v_mfma_f32_16x16x32_bf16 v[42:45], v[208:211], v[152:155], v[42:45]
	v_mfma_f32_16x16x32_bf16 v[34:37], v[212:215], v[152:155], v[34:37]
	v_mfma_f32_16x16x32_bf16 v[30:33], v[188:191], v[156:159], v[30:33]
	v_mfma_f32_16x16x32_bf16 v[22:25], v[192:195], v[156:159], v[22:25]
	v_mfma_f32_16x16x32_bf16 v[26:29], v[208:211], v[156:159], v[26:29]
	v_mfma_f32_16x16x32_bf16 v[18:21], v[212:215], v[156:159], v[18:21]
	v_mfma_f32_16x16x32_bf16 v[14:17], v[188:191], v[160:163], v[14:17]
	v_mfma_f32_16x16x32_bf16 v[6:9], v[192:195], v[160:163], v[6:9]
	v_mfma_f32_16x16x32_bf16 v[10:13], v[208:211], v[160:163], v[10:13]
	v_mfma_f32_16x16x32_bf16 v[2:5], v[212:215], v[160:163], v[2:5]
	s_waitcnt lgkmcnt(0)
	v_mfma_f32_16x16x32_bf16 v[66:69], v[188:191], v[164:167], v[66:69]
	v_mfma_f32_16x16x32_bf16 v[70:73], v[192:195], v[164:167], v[70:73]
	v_mfma_f32_16x16x32_bf16 v[82:85], v[208:211], v[164:167], v[82:85]
	v_mfma_f32_16x16x32_bf16 v[86:89], v[212:215], v[164:167], v[86:89]
	v_mfma_f32_16x16x32_bf16 v[90:93], v[188:191], v[168:171], v[90:93]
	v_mfma_f32_16x16x32_bf16 v[94:97], v[192:195], v[168:171], v[94:97]
	v_mfma_f32_16x16x32_bf16 v[98:101], v[208:211], v[168:171], v[98:101]
	v_mfma_f32_16x16x32_bf16 v[102:105], v[212:215], v[168:171], v[102:105]
	v_mfma_f32_16x16x32_bf16 v[106:109], v[188:191], v[174:177], v[106:109]
	v_mfma_f32_16x16x32_bf16 v[110:113], v[192:195], v[174:177], v[110:113]
	v_mfma_f32_16x16x32_bf16 v[114:117], v[208:211], v[174:177], v[114:117]
	v_mfma_f32_16x16x32_bf16 v[118:121], v[212:215], v[174:177], v[118:121]
	v_mfma_f32_16x16x32_bf16 v[122:125], v[188:191], v[182:185], v[122:125]
	v_mfma_f32_16x16x32_bf16 v[126:129], v[192:195], v[182:185], v[126:129]
	v_mfma_f32_16x16x32_bf16 v[136:139], v[208:211], v[182:185], v[136:139]
	v_mfma_f32_16x16x32_bf16 v[140:143], v[212:215], v[182:185], v[140:143]
	s_setprio 0
	ds_read_b128 v[148:151], v81 offset:0
	ds_read_b128 v[152:155], v81 offset:2048
	ds_read_b128 v[156:159], v81 offset:4096
	ds_read_b128 v[160:163], v81 offset:6144
	ds_read_b128 v[188:191], v145 offset:49152
	ds_read_b128 v[192:195], v145 offset:51200
	ds_read_b128 v[208:211], v145 offset:53248
	ds_read_b128 v[212:215], v145 offset:55296
	ds_read_b128 v[164:167], v81 offset:16384
	ds_read_b128 v[168:171], v81 offset:18432
	ds_read_b128 v[174:177], v81 offset:20480
	ds_read_b128 v[182:185], v81 offset:22528
	s_waitcnt lgkmcnt(0)
	s_barrier
	s_add_i32 m0, s64, 0x0
	s_nop 0
	global_load_lds_dwordx4 v76, s[50:51]
	s_add_i32 m0, s64, 0x1000
	s_nop 0
	global_load_lds_dwordx4 v77, s[50:51]
	s_add_i32 m0, s64, 0x2000
	s_nop 0
	global_load_lds_dwordx4 v78, s[50:51]
	s_add_i32 m0, s64, 0x3000
	s_nop 0
	global_load_lds_dwordx4 v79, s[50:51]
	s_add_i32 m0, s64, 0x4000
	s_nop 0
	global_load_lds_dwordx4 v76, s[52:53]
	s_add_i32 m0, s64, 0x5000
	s_nop 0
	global_load_lds_dwordx4 v77, s[52:53]
	s_add_i32 m0, s64, 0x6000
	s_nop 0
	global_load_lds_dwordx4 v78, s[52:53]
	s_add_i32 m0, s64, 0x7000
	s_nop 0
	global_load_lds_dwordx4 v79, s[52:53]
	s_add_u32 s50, s50, 0x80
	s_addc_u32 s51, s51, 0
	s_add_u32 s52, s52, 0x80
	s_addc_u32 s53, s53, 0
	s_setprio 1
	v_mfma_f32_16x16x32_bf16 v[62:65], v[188:191], v[148:151], v[62:65]
	v_mfma_f32_16x16x32_bf16 v[54:57], v[192:195], v[148:151], v[54:57]
	v_mfma_f32_16x16x32_bf16 v[58:61], v[208:211], v[148:151], v[58:61]
	v_mfma_f32_16x16x32_bf16 v[50:53], v[212:215], v[148:151], v[50:53]
	v_mfma_f32_16x16x32_bf16 v[46:49], v[188:191], v[152:155], v[46:49]
	v_mfma_f32_16x16x32_bf16 v[38:41], v[192:195], v[152:155], v[38:41]
	v_mfma_f32_16x16x32_bf16 v[42:45], v[208:211], v[152:155], v[42:45]
	v_mfma_f32_16x16x32_bf16 v[34:37], v[212:215], v[152:155], v[34:37]
	v_mfma_f32_16x16x32_bf16 v[30:33], v[188:191], v[156:159], v[30:33]
	v_mfma_f32_16x16x32_bf16 v[22:25], v[192:195], v[156:159], v[22:25]
	v_mfma_f32_16x16x32_bf16 v[26:29], v[208:211], v[156:159], v[26:29]
	v_mfma_f32_16x16x32_bf16 v[18:21], v[212:215], v[156:159], v[18:21]
	v_mfma_f32_16x16x32_bf16 v[14:17], v[188:191], v[160:163], v[14:17]
	v_mfma_f32_16x16x32_bf16 v[6:9], v[192:195], v[160:163], v[6:9]
	v_mfma_f32_16x16x32_bf16 v[10:13], v[208:211], v[160:163], v[10:13]
	v_mfma_f32_16x16x32_bf16 v[2:5], v[212:215], v[160:163], v[2:5]
	v_mfma_f32_16x16x32_bf16 v[66:69], v[188:191], v[164:167], v[66:69]
	v_mfma_f32_16x16x32_bf16 v[70:73], v[192:195], v[164:167], v[70:73]
	v_mfma_f32_16x16x32_bf16 v[82:85], v[208:211], v[164:167], v[82:85]
	v_mfma_f32_16x16x32_bf16 v[86:89], v[212:215], v[164:167], v[86:89]
	v_mfma_f32_16x16x32_bf16 v[90:93], v[188:191], v[168:171], v[90:93]
	v_mfma_f32_16x16x32_bf16 v[94:97], v[192:195], v[168:171], v[94:97]
	v_mfma_f32_16x16x32_bf16 v[98:101], v[208:211], v[168:171], v[98:101]
	v_mfma_f32_16x16x32_bf16 v[102:105], v[212:215], v[168:171], v[102:105]
	v_mfma_f32_16x16x32_bf16 v[106:109], v[188:191], v[174:177], v[106:109]
	v_mfma_f32_16x16x32_bf16 v[110:113], v[192:195], v[174:177], v[110:113]
	v_mfma_f32_16x16x32_bf16 v[114:117], v[208:211], v[174:177], v[114:117]
	v_mfma_f32_16x16x32_bf16 v[118:121], v[212:215], v[174:177], v[118:121]
	v_mfma_f32_16x16x32_bf16 v[122:125], v[188:191], v[182:185], v[122:125]
	v_mfma_f32_16x16x32_bf16 v[126:129], v[192:195], v[182:185], v[126:129]
	v_mfma_f32_16x16x32_bf16 v[136:139], v[208:211], v[182:185], v[136:139]
	v_mfma_f32_16x16x32_bf16 v[140:143], v[212:215], v[182:185], v[140:143]
	s_setprio 0
	s_add_i32 s65, s65, -1
	s_cmp_lg_u32 s65, 0
	s_cbranch_scc1 .Lf2_k
	s_waitcnt vmcnt(0)
	s_barrier
	s_add_i32 m0, s64, 0xc000
	s_nop 0
	global_load_lds_dwordx4 v76, s[58:59]
	s_add_i32 m0, s64, 0xd000
	s_nop 0
	global_load_lds_dwordx4 v77, s[58:59]
	s_add_i32 m0, s64, 0xe000
	s_nop 0
	global_load_lds_dwordx4 v78, s[58:59]
	s_add_i32 m0, s64, 0xf000
	s_nop 0
	global_load_lds_dwordx4 v79, s[58:59]
	s_add_u32 s58, s58, 0x80
	s_addc_u32 s59, s59, 0
	ds_read_b128 v[148:151], v80 offset:0
	ds_read_b128 v[152:155], v80 offset:2048
	ds_read_b128 v[156:159], v80 offset:4096
	ds_read_b128 v[160:163], v80 offset:6144
	ds_read_b128 v[188:191], v144 offset:32768
	ds_read_b128 v[192:195], v144 offset:34816
	ds_read_b128 v[208:211], v144 offset:36864
	ds_read_b128 v[212:215], v144 offset:38912
	ds_read_b128 v[164:167], v80 offset:16384
	ds_read_b128 v[168:171], v80 offset:18432
	ds_read_b128 v[174:177], v80 offset:20480
	ds_read_b128 v[182:185], v80 offset:22528
	s_setprio 1
	s_waitcnt lgkmcnt(4)
	v_mfma_f32_16x16x32_bf16 v[62:65], v[188:191], v[148:151], v[62:65]
	v_mfma_f32_16x16x32_bf16 v[54:57], v[192:195], v[148:151], v[54:57]
	v_mfma_f32_16x16x32_bf16 v[58:61], v[208:211], v[148:151], v[58:61]
	v_mfma_f32_16x16x32_bf16 v[50:53], v[212:215], v[148:151], v[50:53]
	v_mfma_f32_16x16x32_bf16 v[46:49], v[188:191], v[152:155], v[46:49]
	v_mfma_f32_16x16x32_bf16 v[38:41], v[192:195], v[152:155], v[38:41]
	v_mfma_f32_16x16x32_bf16 v[42:45], v[208:211], v[152:155], v[42:45]
	v_mfma_f32_16x16x32_bf16 v[34:37], v[212:215], v[152:155], v[34:37]
	v_mfma_f32_16x16x32_bf16 v[30:33], v[188:191], v[156:159], v[30:33]
	v_mfma_f32_16x16x32_bf16 v[22:25], v[192:195], v[156:159], v[22:25]
	v_mfma_f32_16x16x32_bf16 v[26:29], v[208:211], v[156:159], v[26:29]
	v_mfma_f32_16x16x32_bf16 v[18:21], v[212:215], v[156:159], v[18:21]
	v_mfma_f32_16x16x32_bf16 v[14:17], v[188:191], v[160:163], v[14:17]
	v_mfma_f32_16x16x32_bf16 v[6:9], v[192:195], v[160:163], v[6:9]
	v_mfma_f32_16x16x32_bf16 v[10:13], v[208:211], v[160:163], v[10:13]
	v_mfma_f32_16x16x32_bf16 v[2:5], v[212:215], v[160:163], v[2:5]
	s_waitcnt lgkmcnt(0)
	v_mfma_f32_16x16x32_bf16 v[66:69], v[188:191], v[164:167], v[66:69]
	v_mfma_f32_16x16x32_bf16 v[70:73], v[192:195], v[164:167], v[70:73]
	v_mfma_f32_16x16x32_bf16 v[82:85], v[208:211], v[164:167], v[82:85]
	v_mfma_f32_16x16x32_bf16 v[86:89], v[212:215], v[164:167], v[86:89]
	v_mfma_f32_16x16x32_bf16 v[90:93], v[188:191], v[168:171], v[90:93]
	v_mfma_f32_16x16x32_bf16 v[94:97], v[192:195], v[168:171], v[94:97]
	v_mfma_f32_16x16x32_bf16 v[98:101], v[208:211], v[168:171], v[98:101]
	v_mfma_f32_16x16x32_bf16 v[102:105], v[212:215], v[168:171], v[102:105]
	v_mfma_f32_16x16x32_bf16 v[106:109], v[188:191], v[174:177], v[106:109]
	v_mfma_f32_16x16x32_bf16 v[110:113], v[192:195], v[174:177], v[110:113]
	v_mfma_f32_16x16x32_bf16 v[114:117], v[208:211], v[174:177], v[114:117]
	v_mfma_f32_16x16x32_bf16 v[118:121], v[212:215], v[174:177], v[118:121]
	v_mfma_f32_16x16x32_bf16 v[122:125], v[188:191], v[182:185], v[122:125]
	v_mfma_f32_16x16x32_bf16 v[126:129], v[192:195], v[182:185], v[126:129]
	v_mfma_f32_16x16x32_bf16 v[136:139], v[208:211], v[182:185], v[136:139]
	v_mfma_f32_16x16x32_bf16 v[140:143], v[212:215], v[182:185], v[140:143]
	s_setprio 0
	ds_read_b128 v[148:151], v81 offset:0
	ds_read_b128 v[152:155], v81 offset:2048
	ds_read_b128 v[156:159], v81 offset:4096
	ds_read_b128 v[160:163], v81 offset:6144
	ds_read_b128 v[188:191], v145 offset:32768
	ds_read_b128 v[192:195], v145 offset:34816
	ds_read_b128 v[208:211], v145 offset:36864
	ds_read_b128 v[212:215], v145 offset:38912
	ds_read_b128 v[164:167], v81 offset:16384
	ds_read_b128 v[168:171], v81 offset:18432
	ds_read_b128 v[174:177], v81 offset:20480
	ds_read_b128 v[182:185], v81 offset:22528
	s_waitcnt lgkmcnt(0)
	s_barrier
	s_add_i32 m0, s64, 0x0
	s_nop 0
	global_load_lds_dwordx4 v76, s[50:51]
	s_add_i32 m0, s64, 0x1000
	s_nop 0
	global_load_lds_dwordx4 v77, s[50:51]
	s_add_i32 m0, s64, 0x2000
	s_nop 0
	global_load_lds_dwordx4 v78, s[50:51]
	s_add_i32 m0, s64, 0x3000
	s_nop 0
	global_load_lds_dwordx4 v79, s[50:51]
	s_add_i32 m0, s64, 0x4000
	s_nop 0
	global_load_lds_dwordx4 v76, s[52:53]
	s_add_i32 m0, s64, 0x5000
	s_nop 0
	global_load_lds_dwordx4 v77, s[52:53]
	s_add_i32 m0, s64, 0x6000
	s_nop 0
	global_load_lds_dwordx4 v78, s[52:53]
	s_add_i32 m0, s64, 0x7000
	s_nop 0
	global_load_lds_dwordx4 v79, s[52:53]
	s_add_u32 s50, s50, 0x80
	s_addc_u32 s51, s51, 0
	s_add_u32 s52, s52, 0x80
	s_addc_u32 s53, s53, 0
	s_setprio 1
	v_mfma_f32_16x16x32_bf16 v[62:65], v[188:191], v[148:151], v[62:65]
	v_mfma_f32_16x16x32_bf16 v[54:57], v[192:195], v[148:151], v[54:57]
	v_mfma_f32_16x16x32_bf16 v[58:61], v[208:211], v[148:151], v[58:61]
	v_mfma_f32_16x16x32_bf16 v[50:53], v[212:215], v[148:151], v[50:53]
	v_mfma_f32_16x16x32_bf16 v[46:49], v[188:191], v[152:155], v[46:49]
	v_mfma_f32_16x16x32_bf16 v[38:41], v[192:195], v[152:155], v[38:41]
	v_mfma_f32_16x16x32_bf16 v[42:45], v[208:211], v[152:155], v[42:45]
	v_mfma_f32_16x16x32_bf16 v[34:37], v[212:215], v[152:155], v[34:37]
	v_mfma_f32_16x16x32_bf16 v[30:33], v[188:191], v[156:159], v[30:33]
	v_mfma_f32_16x16x32_bf16 v[22:25], v[192:195], v[156:159], v[22:25]
	v_mfma_f32_16x16x32_bf16 v[26:29], v[208:211], v[156:159], v[26:29]
	v_mfma_f32_16x16x32_bf16 v[18:21], v[212:215], v[156:159], v[18:21]
	v_mfma_f32_16x16x32_bf16 v[14:17], v[188:191], v[160:163], v[14:17]
	v_mfma_f32_16x16x32_bf16 v[6:9], v[192:195], v[160:163], v[6:9]
	v_mfma_f32_16x16x32_bf16 v[10:13], v[208:211], v[160:163], v[10:13]
	v_mfma_f32_16x16x32_bf16 v[2:5], v[212:215], v[160:163], v[2:5]
	v_mfma_f32_16x16x32_bf16 v[66:69], v[188:191], v[164:167], v[66:69]
	v_mfma_f32_16x16x32_bf16 v[70:73], v[192:195], v[164:167], v[70:73]
	v_mfma_f32_16x16x32_bf16 v[82:85], v[208:211], v[164:167], v[82:85]
	v_mfma_f32_16x16x32_bf16 v[86:89], v[212:215], v[164:167], v[86:89]
	v_mfma_f32_16x16x32_bf16 v[90:93], v[188:191], v[168:171], v[90:93]
	v_mfma_f32_16x16x32_bf16 v[94:97], v[192:195], v[168:171], v[94:97]
	v_mfma_f32_16x16x32_bf16 v[98:101], v[208:211], v[168:171], v[98:101]
	v_mfma_f32_16x16x32_bf16 v[102:105], v[212:215], v[168:171], v[102:105]
	v_mfma_f32_16x16x32_bf16 v[106:109], v[188:191], v[174:177], v[106:109]
	v_mfma_f32_16x16x32_bf16 v[110:113], v[192:195], v[174:177], v[110:113]
	v_mfma_f32_16x16x32_bf16 v[114:117], v[208:211], v[174:177], v[114:117]
	v_mfma_f32_16x16x32_bf16 v[118:121], v[212:215], v[174:177], v[118:121]
	v_mfma_f32_16x16x32_bf16 v[122:125], v[188:191], v[182:185], v[122:125]
	v_mfma_f32_16x16x32_bf16 v[126:129], v[192:195], v[182:185], v[126:129]
	v_mfma_f32_16x16x32_bf16 v[136:139], v[208:211], v[182:185], v[136:139]
	v_mfma_f32_16x16x32_bf16 v[140:143], v[212:215], v[182:185], v[140:143]
	s_setprio 0
	s_waitcnt vmcnt(0)
	s_barrier
	ds_read_b128 v[148:151], v80 offset:0
	ds_read_b128 v[152:155], v80 offset:2048
	ds_read_b128 v[156:159], v80 offset:4096
	ds_read_b128 v[160:163], v80 offset:6144
	ds_read_b128 v[188:191], v144 offset:49152
	ds_read_b128 v[192:195], v144 offset:51200
	ds_read_b128 v[208:211], v144 offset:53248
	ds_read_b128 v[212:215], v144 offset:55296
	ds_read_b128 v[164:167], v80 offset:16384
	ds_read_b128 v[168:171], v80 offset:18432
	ds_read_b128 v[174:177], v80 offset:20480
	ds_read_b128 v[182:185], v80 offset:22528
	s_setprio 1
	s_waitcnt lgkmcnt(4)
	v_mfma_f32_16x16x32_bf16 v[62:65], v[188:191], v[148:151], v[62:65]
	v_mfma_f32_16x16x32_bf16 v[54:57], v[192:195], v[148:151], v[54:57]
	v_mfma_f32_16x16x32_bf16 v[58:61], v[208:211], v[148:151], v[58:61]
	v_mfma_f32_16x16x32_bf16 v[50:53], v[212:215], v[148:151], v[50:53]
	v_mfma_f32_16x16x32_bf16 v[46:49], v[188:191], v[152:155], v[46:49]
	v_mfma_f32_16x16x32_bf16 v[38:41], v[192:195], v[152:155], v[38:41]
	v_mfma_f32_16x16x32_bf16 v[42:45], v[208:211], v[152:155], v[42:45]
	v_mfma_f32_16x16x32_bf16 v[34:37], v[212:215], v[152:155], v[34:37]
	v_mfma_f32_16x16x32_bf16 v[30:33], v[188:191], v[156:159], v[30:33]
	v_mfma_f32_16x16x32_bf16 v[22:25], v[192:195], v[156:159], v[22:25]
	v_mfma_f32_16x16x32_bf16 v[26:29], v[208:211], v[156:159], v[26:29]
	v_mfma_f32_16x16x32_bf16 v[18:21], v[212:215], v[156:159], v[18:21]
	v_mfma_f32_16x16x32_bf16 v[14:17], v[188:191], v[160:163], v[14:17]
	v_mfma_f32_16x16x32_bf16 v[6:9], v[192:195], v[160:163], v[6:9]
	v_mfma_f32_16x16x32_bf16 v[10:13], v[208:211], v[160:163], v[10:13]
	v_mfma_f32_16x16x32_bf16 v[2:5], v[212:215], v[160:163], v[2:5]
	s_waitcnt lgkmcnt(0)
	v_mfma_f32_16x16x32_bf16 v[66:69], v[188:191], v[164:167], v[66:69]
	v_mfma_f32_16x16x32_bf16 v[70:73], v[192:195], v[164:167], v[70:73]
	v_mfma_f32_16x16x32_bf16 v[82:85], v[208:211], v[164:167], v[82:85]
	v_mfma_f32_16x16x32_bf16 v[86:89], v[212:215], v[164:167], v[86:89]
	v_mfma_f32_16x16x32_bf16 v[90:93], v[188:191], v[168:171], v[90:93]
	v_mfma_f32_16x16x32_bf16 v[94:97], v[192:195], v[168:171], v[94:97]
	v_mfma_f32_16x16x32_bf16 v[98:101], v[208:211], v[168:171], v[98:101]
	v_mfma_f32_16x16x32_bf16 v[102:105], v[212:215], v[168:171], v[102:105]
	v_mfma_f32_16x16x32_bf16 v[106:109], v[188:191], v[174:177], v[106:109]
	v_mfma_f32_16x16x32_bf16 v[110:113], v[192:195], v[174:177], v[110:113]
	v_mfma_f32_16x16x32_bf16 v[114:117], v[208:211], v[174:177], v[114:117]
	v_mfma_f32_16x16x32_bf16 v[118:121], v[212:215], v[174:177], v[118:121]
	v_mfma_f32_16x16x32_bf16 v[122:125], v[188:191], v[182:185], v[122:125]
	v_mfma_f32_16x16x32_bf16 v[126:129], v[192:195], v[182:185], v[126:129]
	v_mfma_f32_16x16x32_bf16 v[136:139], v[208:211], v[182:185], v[136:139]
	v_mfma_f32_16x16x32_bf16 v[140:143], v[212:215], v[182:185], v[140:143]
	s_setprio 0
	ds_read_b128 v[148:151], v81 offset:0
	ds_read_b128 v[152:155], v81 offset:2048
	ds_read_b128 v[156:159], v81 offset:4096
	ds_read_b128 v[160:163], v81 offset:6144
	ds_read_b128 v[188:191], v145 offset:49152
	ds_read_b128 v[192:195], v145 offset:51200
	ds_read_b128 v[208:211], v145 offset:53248
	ds_read_b128 v[212:215], v145 offset:55296
	ds_read_b128 v[164:167], v81 offset:16384
	ds_read_b128 v[168:171], v81 offset:18432
	ds_read_b128 v[174:177], v81 offset:20480
	ds_read_b128 v[182:185], v81 offset:22528
	s_setprio 1
	s_waitcnt lgkmcnt(4)
	v_mfma_f32_16x16x32_bf16 v[62:65], v[188:191], v[148:151], v[62:65]
	v_mfma_f32_16x16x32_bf16 v[54:57], v[192:195], v[148:151], v[54:57]
	v_mfma_f32_16x16x32_bf16 v[58:61], v[208:211], v[148:151], v[58:61]
	v_mfma_f32_16x16x32_bf16 v[50:53], v[212:215], v[148:151], v[50:53]
	v_mfma_f32_16x16x32_bf16 v[46:49], v[188:191], v[152:155], v[46:49]
	v_mfma_f32_16x16x32_bf16 v[38:41], v[192:195], v[152:155], v[38:41]
	v_mfma_f32_16x16x32_bf16 v[42:45], v[208:211], v[152:155], v[42:45]
	v_mfma_f32_16x16x32_bf16 v[34:37], v[212:215], v[152:155], v[34:37]
	v_mfma_f32_16x16x32_bf16 v[30:33], v[188:191], v[156:159], v[30:33]
	v_mfma_f32_16x16x32_bf16 v[22:25], v[192:195], v[156:159], v[22:25]
	v_mfma_f32_16x16x32_bf16 v[26:29], v[208:211], v[156:159], v[26:29]
	v_mfma_f32_16x16x32_bf16 v[18:21], v[212:215], v[156:159], v[18:21]
	v_mfma_f32_16x16x32_bf16 v[14:17], v[188:191], v[160:163], v[14:17]
	v_mfma_f32_16x16x32_bf16 v[6:9], v[192:195], v[160:163], v[6:9]
	v_mfma_f32_16x16x32_bf16 v[10:13], v[208:211], v[160:163], v[10:13]
	v_mfma_f32_16x16x32_bf16 v[2:5], v[212:215], v[160:163], v[2:5]
	s_waitcnt lgkmcnt(0)
	v_mfma_f32_16x16x32_bf16 v[66:69], v[188:191], v[164:167], v[66:69]
	v_mfma_f32_16x16x32_bf16 v[70:73], v[192:195], v[164:167], v[70:73]
	v_mfma_f32_16x16x32_bf16 v[82:85], v[208:211], v[164:167], v[82:85]
	v_mfma_f32_16x16x32_bf16 v[86:89], v[212:215], v[164:167], v[86:89]
	v_mfma_f32_16x16x32_bf16 v[90:93], v[188:191], v[168:171], v[90:93]
	v_mfma_f32_16x16x32_bf16 v[94:97], v[192:195], v[168:171], v[94:97]
	v_mfma_f32_16x16x32_bf16 v[98:101], v[208:211], v[168:171], v[98:101]
	v_mfma_f32_16x16x32_bf16 v[102:105], v[212:215], v[168:171], v[102:105]
	v_mfma_f32_16x16x32_bf16 v[106:109], v[188:191], v[174:177], v[106:109]
	v_mfma_f32_16x16x32_bf16 v[110:113], v[192:195], v[174:177], v[110:113]
	v_mfma_f32_16x16x32_bf16 v[114:117], v[208:211], v[174:177], v[114:117]
	v_mfma_f32_16x16x32_bf16 v[118:121], v[212:215], v[174:177], v[118:121]
	v_mfma_f32_16x16x32_bf16 v[122:125], v[188:191], v[182:185], v[122:125]
	v_mfma_f32_16x16x32_bf16 v[126:129], v[192:195], v[182:185], v[126:129]
	v_mfma_f32_16x16x32_bf16 v[136:139], v[208:211], v[182:185], v[136:139]
	v_mfma_f32_16x16x32_bf16 v[140:143], v[212:215], v[182:185], v[140:143]
	s_setprio 0
	s_nop 7
	s_nop 7
	s_nop 7
	v_mov_b32_e32 v148, v66
	v_mov_b32_e32 v149, v67
	v_mov_b32_e32 v150, v68
	v_mov_b32_e32 v151, v69
	v_mov_b32_e32 v152, v70
	v_mov_b32_e32 v153, v71
	v_mov_b32_e32 v154, v72
	v_mov_b32_e32 v155, v73
	v_mov_b32_e32 v156, v82
	v_mov_b32_e32 v157, v83
	v_mov_b32_e32 v158, v84
	v_mov_b32_e32 v159, v85
	v_mov_b32_e32 v160, v86
	v_mov_b32_e32 v161, v87
	v_mov_b32_e32 v162, v88
	v_mov_b32_e32 v163, v89
	v_mov_b32_e32 v164, v90
	v_mov_b32_e32 v165, v91
	v_mov_b32_e32 v166, v92
	v_mov_b32_e32 v167, v93
	v_mov_b32_e32 v168, v94
	v_mov_b32_e32 v169, v95
	v_mov_b32_e32 v170, v96
	v_mov_b32_e32 v171, v97
	v_mov_b32_e32 v174, v98
	v_mov_b32_e32 v175, v99
	v_mov_b32_e32 v176, v100
	v_mov_b32_e32 v177, v101
	v_mov_b32_e32 v182, v102
	v_mov_b32_e32 v183, v103
	v_mov_b32_e32 v184, v104
	v_mov_b32_e32 v185, v105
	v_mov_b32_e32 v188, v106
	v_mov_b32_e32 v189, v107
	v_mov_b32_e32 v190, v108
	v_mov_b32_e32 v191, v109
	v_mov_b32_e32 v192, v110
	v_mov_b32_e32 v193, v111
	v_mov_b32_e32 v194, v112
	v_mov_b32_e32 v195, v113
	v_mov_b32_e32 v208, v114
	v_mov_b32_e32 v209, v115
	v_mov_b32_e32 v210, v116
	v_mov_b32_e32 v211, v117
	v_mov_b32_e32 v212, v118
	v_mov_b32_e32 v213, v119
	v_mov_b32_e32 v214, v120
	v_mov_b32_e32 v215, v121
	v_mov_b32_e32 v216, v122
	v_mov_b32_e32 v217, v123
	v_mov_b32_e32 v218, v124
	v_mov_b32_e32 v219, v125
	v_mov_b32_e32 v220, v126
	v_mov_b32_e32 v221, v127
	v_mov_b32_e32 v222, v128
	v_mov_b32_e32 v223, v129
	v_mov_b32_e32 v242, v136
	v_mov_b32_e32 v243, v137
	v_mov_b32_e32 v244, v138
	v_mov_b32_e32 v245, v139
	v_mov_b32_e32 v199, v140
	v_mov_b32_e32 v206, v141
	v_mov_b32_e32 v207, v142
	v_mov_b32_e32 v226, v143
	s_add_i32 s48, s48, 1
	s_mov_b32 s39, 0
	v_readlane_b32 s30, v249, 0
	s_nop 0
	s_and_b32 s31, s30, 7
	s_lshr_b32 s30, s30, 3
	s_cmp_lt_u32 s30, 32
	s_cselect_b32 s35, 6, 5
	s_cmp_lt_u32 s48, s35
	s_cbranch_scc0 .Lf2_c1_extra
	s_lshl_b32 s33, s48, 6
	s_add_i32 s33, s33, s30
	s_cmp_ge_u32 s33, 0xb0
	s_cselect_b32 s34, 1, 0
	s_mul_i32 s36, s34, 0xb0
	s_sub_i32 s33, s33, s36
	s_lshr_b32 s37, s33, 2
	s_and_b32 s33, s33, 3
	s_lshl_b32 s34, s34, 3
	s_add_i32 s33, s33, s34
	s_lshl_b32 s33, s33, 3
	s_add_i32 s36, s33, s31
	s_add_i32 s38, s36, 32
	s_branch .Lf2_c1_have
.Lf2_c1_extra:
	s_cmp_eq_u32 s48, s35
	s_cbranch_scc0 .Lf2_nopf
	s_cmp_lt_u32 s30, 32
	s_cbranch_scc1 .Lf2_nopf
	s_sub_i32 s33, s30, 32
	s_lshl_b32 s33, s33, 3
	s_add_i32 s37, s33, s31
	s_cmp_lt_u32 s37, 44
	s_cbranch_scc0 .Lf2_nopf
	s_movk_i32 s36, 0x80
	s_movk_i32 s38, 0x81
.Lf2_c1_have:
	s_mov_b32 s39, 2
	s_lshl_b32 s30, s36, 18
	s_add_u32 s50, s6, s30
	s_addc_u32 s51, s7, 0
	s_lshl_b32 s30, s38, 18
	s_add_u32 s52, s6, s30
	s_addc_u32 s53, s7, 0
	s_lshl_b32 s30, s37, 18
	s_add_u32 s58, s19, s30
	s_addc_u32 s59, s20, 0
	s_barrier
	s_add_i32 m0, s64, 0x0
	s_nop 0
	global_load_lds_dwordx4 v76, s[50:51]
	s_add_i32 m0, s64, 0x1000
	s_nop 0
	global_load_lds_dwordx4 v77, s[50:51]
	s_add_i32 m0, s64, 0x2000
	s_nop 0
	global_load_lds_dwordx4 v78, s[50:51]
	s_add_i32 m0, s64, 0x3000
	s_nop 0
	global_load_lds_dwordx4 v79, s[50:51]
	s_add_i32 m0, s64, 0x4000
	s_nop 0
	global_load_lds_dwordx4 v76, s[52:53]
	s_add_i32 m0, s64, 0x5000
	s_nop 0
	global_load_lds_dwordx4 v77, s[52:53]
	s_add_i32 m0, s64, 0x6000
	s_nop 0
	global_load_lds_dwordx4 v78, s[52:53]
	s_add_i32 m0, s64, 0x7000
	s_nop 0
	global_load_lds_dwordx4 v79, s[52:53]
	s_add_u32 s50, s50, 0x80
	s_addc_u32 s51, s51, 0
	s_add_u32 s52, s52, 0x80
	s_addc_u32 s53, s53, 0
	s_add_i32 m0, s64, 0x8000
	s_nop 0
	global_load_lds_dwordx4 v76, s[58:59]
	s_add_i32 m0, s64, 0x9000
	s_nop 0
	global_load_lds_dwordx4 v77, s[58:59]
	s_add_i32 m0, s64, 0xa000
	s_nop 0
	global_load_lds_dwordx4 v78, s[58:59]
	s_add_i32 m0, s64, 0xb000
	s_nop 0
	global_load_lds_dwordx4 v79, s[58:59]
	s_add_u32 s58, s58, 0x80
	s_addc_u32 s59, s59, 0

.Lf2_next:
	s_cmp_eq_u32 s39, 0
	s_cbranch_scc1 .Lf2_done
	s_mov_b32 s8, s36
	s_mov_b32 s21, s37
	s_mov_b32 s49, s38
	s_branch .Lf2_setup
